# W_o / FFN2 residual epilogue: all 16 pieces (and gamma/beta/stat) loaded up front into v2..v65, one round trip instead of four
# speedup vs baseline: 1.0092x; 1.0085x over previous
.LBB0_128:
	s_setprio 1
	s_add_u32 s98, s42, s27
	s_addc_u32 s99, s43, 0
	s_add_u32 s98, s98, 0x80
	s_addc_u32 s99, s99, 0
	ds_read_b128 v[132:135], v127 offset:16384
	ds_read_b128 v[140:143], v129
	ds_read_b128 v[152:155], v127 offset:18432
	ds_read_b128 v[160:163], v127 offset:20480
	ds_read_b128 v[164:167], v127 offset:22528
	ds_read_b128 v[144:147], v129 offset:2048
	ds_read_b128 v[148:151], v129 offset:4096
	ds_read_b128 v[156:159], v129 offset:6144
	s_add_u32 m0, s100, 0x8000
	s_waitcnt lgkmcnt(6)
	v_mfma_f32_16x16x32_bf16 v[34:37], v[132:135], v[140:143], v[34:37]
	global_load_lds_dwordx4 v194, s[98:99]
	s_waitcnt lgkmcnt(5)
	v_mfma_f32_16x16x32_bf16 v[94:97], v[152:155], v[140:143], v[94:97]
	ds_read_b128 v[198:201], v128
	s_add_u32 m0, s100, 0xc000
	s_waitcnt lgkmcnt(5)
	v_mfma_f32_16x16x32_bf16 v[38:41], v[160:163], v[140:143], v[38:41]
	global_load_lds_dwordx4 v195, s[98:99]
	s_waitcnt lgkmcnt(4)
	v_mfma_f32_16x16x32_bf16 v[90:93], v[164:167], v[140:143], v[90:93]
	ds_read_b128 v[140:143], v128 offset:2048
	s_add_u32 m0, s100, 0x9000
	s_waitcnt lgkmcnt(4)
	v_mfma_f32_16x16x32_bf16 v[42:45], v[132:135], v[144:147], v[42:45]
	global_load_lds_dwordx4 v196, s[98:99]
	v_mfma_f32_16x16x32_bf16 v[86:89], v[152:155], v[144:147], v[86:89]
	ds_read_b128 v[210:213], v128 offset:4096
	s_add_u32 m0, s100, 0xd000
	v_mfma_f32_16x16x32_bf16 v[46:49], v[160:163], v[144:147], v[46:49]
	global_load_lds_dwordx4 v197, s[98:99]
	v_mfma_f32_16x16x32_bf16 v[82:85], v[164:167], v[144:147], v[82:85]
	ds_read_b128 v[144:147], v128 offset:6144
	s_add_u32 m0, s100, 0xa000
	s_waitcnt lgkmcnt(5)
	v_mfma_f32_16x16x32_bf16 v[50:53], v[132:135], v[148:151], v[50:53]
	global_load_lds_dwordx4 v202, s[98:99]
	v_mfma_f32_16x16x32_bf16 v[78:81], v[152:155], v[148:151], v[78:81]
	ds_read_b128 v[222:225], v130 offset:16384
	s_add_u32 m0, s100, 0xe000
	v_mfma_f32_16x16x32_bf16 v[54:57], v[160:163], v[148:151], v[54:57]
	global_load_lds_dwordx4 v203, s[98:99]
	v_mfma_f32_16x16x32_bf16 v[70:73], v[164:167], v[148:151], v[70:73]
	ds_read_b128 v[148:151], v130 offset:18432
	s_add_u32 m0, s100, 0xb000
	s_waitcnt lgkmcnt(6)
	v_mfma_f32_16x16x32_bf16 v[58:61], v[132:135], v[156:159], v[58:61]
	global_load_lds_dwordx4 v204, s[98:99]
	v_mfma_f32_16x16x32_bf16 v[66:69], v[152:155], v[156:159], v[66:69]
	ds_read_b128 v[152:155], v130 offset:20480
	s_add_u32 m0, s100, 0xf000
	v_mfma_f32_16x16x32_bf16 v[62:65], v[160:163], v[156:159], v[62:65]
	global_load_lds_dwordx4 v205, s[98:99]
	v_mfma_f32_16x16x32_bf16 v[74:77], v[164:167], v[156:159], v[74:77]
	ds_read_b128 v[156:159], v130 offset:22528
	s_waitcnt lgkmcnt(3)
	v_mfma_f32_16x16x32_bf16 v[34:37], v[222:225], v[198:201], v[34:37]
	s_waitcnt lgkmcnt(2)
	v_mfma_f32_16x16x32_bf16 v[94:97], v[148:151], v[198:201], v[94:97]
	s_waitcnt lgkmcnt(1)
	v_mfma_f32_16x16x32_bf16 v[38:41], v[152:155], v[198:201], v[38:41]
	s_waitcnt lgkmcnt(0)
	v_mfma_f32_16x16x32_bf16 v[90:93], v[156:159], v[198:201], v[90:93]
	v_mfma_f32_16x16x32_bf16 v[42:45], v[222:225], v[140:143], v[42:45]
	v_mfma_f32_16x16x32_bf16 v[86:89], v[148:151], v[140:143], v[86:89]
	v_mfma_f32_16x16x32_bf16 v[46:49], v[152:155], v[140:143], v[46:49]
	v_mfma_f32_16x16x32_bf16 v[82:85], v[156:159], v[140:143], v[82:85]
	v_mfma_f32_16x16x32_bf16 v[50:53], v[222:225], v[210:213], v[50:53]
	v_mfma_f32_16x16x32_bf16 v[78:81], v[148:151], v[210:213], v[78:81]
	v_mfma_f32_16x16x32_bf16 v[54:57], v[152:155], v[210:213], v[54:57]
	v_mfma_f32_16x16x32_bf16 v[70:73], v[156:159], v[210:213], v[70:73]
	v_mfma_f32_16x16x32_bf16 v[58:61], v[222:225], v[144:147], v[58:61]
	v_mfma_f32_16x16x32_bf16 v[66:69], v[148:151], v[144:147], v[66:69]
	v_mfma_f32_16x16x32_bf16 v[62:65], v[152:155], v[144:147], v[62:65]
	v_mfma_f32_16x16x32_bf16 v[74:77], v[156:159], v[144:147], v[74:77]
	s_waitcnt vmcnt(0)
	s_setprio 0
	s_waitcnt lgkmcnt(0)
	s_barrier
	s_setprio 1
	s_add_u32 s98, s98, 0x80
	s_addc_u32 s99, s99, 0
	ds_read_b128 v[26:29], v127 offset:49152
	ds_read_b128 v[10:13], v129 offset:32768
	ds_read_b128 v[30:33], v127 offset:51200
	ds_read_b128 v[148:151], v127 offset:53248
	ds_read_b128 v[152:155], v127 offset:55296
	ds_read_b128 v[18:21], v129 offset:34816
	ds_read_b128 v[140:143], v129 offset:36864
	ds_read_b128 v[144:147], v129 offset:38912
	s_add_u32 m0, s100, 0x0
	s_waitcnt lgkmcnt(6)
	v_mfma_f32_16x16x32_bf16 v[34:37], v[26:29], v[10:13], v[34:37]
	global_load_lds_dwordx4 v194, s[98:99]
	s_waitcnt lgkmcnt(5)
	v_mfma_f32_16x16x32_bf16 v[94:97], v[30:33], v[10:13], v[94:97]
	ds_read_b128 v[156:159], v128 offset:32768
	s_add_u32 m0, s100, 0x4000
	s_waitcnt lgkmcnt(5)
	v_mfma_f32_16x16x32_bf16 v[38:41], v[148:151], v[10:13], v[38:41]
	global_load_lds_dwordx4 v195, s[98:99]
	s_waitcnt lgkmcnt(4)
	v_mfma_f32_16x16x32_bf16 v[90:93], v[152:155], v[10:13], v[90:93]
	ds_read_b128 v[164:167], v128 offset:34816
	s_add_u32 m0, s100, 0x1000
	s_waitcnt lgkmcnt(4)
	v_mfma_f32_16x16x32_bf16 v[42:45], v[26:29], v[18:21], v[42:45]
	global_load_lds_dwordx4 v196, s[98:99]
	v_mfma_f32_16x16x32_bf16 v[86:89], v[30:33], v[18:21], v[86:89]
	ds_read_b128 v[198:201], v128 offset:36864
	s_add_u32 m0, s100, 0x5000
	v_mfma_f32_16x16x32_bf16 v[46:49], v[148:151], v[18:21], v[46:49]
	global_load_lds_dwordx4 v197, s[98:99]
	v_mfma_f32_16x16x32_bf16 v[82:85], v[152:155], v[18:21], v[82:85]
	ds_read_b128 v[210:213], v128 offset:38912
	s_add_u32 m0, s100, 0x2000
	s_waitcnt lgkmcnt(5)
	v_mfma_f32_16x16x32_bf16 v[50:53], v[26:29], v[140:143], v[50:53]
	global_load_lds_dwordx4 v202, s[98:99]
	v_mfma_f32_16x16x32_bf16 v[78:81], v[30:33], v[140:143], v[78:81]
	ds_read_b128 v[222:225], v130 offset:49152
	s_add_u32 m0, s100, 0x6000
	v_mfma_f32_16x16x32_bf16 v[54:57], v[148:151], v[140:143], v[54:57]
	global_load_lds_dwordx4 v203, s[98:99]
	v_mfma_f32_16x16x32_bf16 v[70:73], v[152:155], v[140:143], v[70:73]
	ds_read_b128 v[140:143], v130 offset:51200
	s_add_u32 m0, s100, 0x3000
	s_waitcnt lgkmcnt(6)
	v_mfma_f32_16x16x32_bf16 v[58:61], v[26:29], v[144:147], v[58:61]
	global_load_lds_dwordx4 v204, s[98:99]
	v_mfma_f32_16x16x32_bf16 v[66:69], v[30:33], v[144:147], v[66:69]
	ds_read_b128 v[230:233], v130 offset:53248
	s_add_u32 m0, s100, 0x7000
	v_mfma_f32_16x16x32_bf16 v[62:65], v[148:151], v[144:147], v[62:65]
	global_load_lds_dwordx4 v205, s[98:99]
	v_mfma_f32_16x16x32_bf16 v[74:77], v[152:155], v[144:147], v[74:77]
	ds_read_b128 v[144:147], v130 offset:55296
	s_waitcnt lgkmcnt(3)
	v_mfma_f32_16x16x32_bf16 v[34:37], v[222:225], v[156:159], v[34:37]
	s_waitcnt lgkmcnt(2)
	v_mfma_f32_16x16x32_bf16 v[94:97], v[140:143], v[156:159], v[94:97]
	s_waitcnt lgkmcnt(1)
	v_mfma_f32_16x16x32_bf16 v[38:41], v[230:233], v[156:159], v[38:41]
	s_waitcnt lgkmcnt(0)
	v_mfma_f32_16x16x32_bf16 v[90:93], v[144:147], v[156:159], v[90:93]
	v_mfma_f32_16x16x32_bf16 v[42:45], v[222:225], v[164:167], v[42:45]
	v_mfma_f32_16x16x32_bf16 v[86:89], v[140:143], v[164:167], v[86:89]
	v_mfma_f32_16x16x32_bf16 v[46:49], v[230:233], v[164:167], v[46:49]
	v_mfma_f32_16x16x32_bf16 v[82:85], v[144:147], v[164:167], v[82:85]
	v_mfma_f32_16x16x32_bf16 v[50:53], v[222:225], v[198:201], v[50:53]
	v_mfma_f32_16x16x32_bf16 v[78:81], v[140:143], v[198:201], v[78:81]
	v_mfma_f32_16x16x32_bf16 v[54:57], v[230:233], v[198:201], v[54:57]
	v_mfma_f32_16x16x32_bf16 v[70:73], v[144:147], v[198:201], v[70:73]
	v_mfma_f32_16x16x32_bf16 v[58:61], v[222:225], v[210:213], v[58:61]
	v_mfma_f32_16x16x32_bf16 v[66:69], v[140:143], v[210:213], v[66:69]
	v_mfma_f32_16x16x32_bf16 v[62:65], v[230:233], v[210:213], v[62:65]
	v_mfma_f32_16x16x32_bf16 v[74:77], v[144:147], v[210:213], v[74:77]
	s_waitcnt vmcnt(0)
	s_setprio 0
	s_add_i32 s8, s8, 2
	s_add_u32 s42, s42, 0x100
	s_addc_u32 s43, s43, 0
	s_cmp_lt_u32 s8, 40
	s_waitcnt lgkmcnt(0)
	s_barrier
	s_cbranch_scc1 .LBB0_128
	v_mov_b32_e32 v2, v194
	v_mov_b32_e32 v3, v195
	v_mov_b32_e32 v4, v196
	v_mov_b32_e32 v5, v197
	v_mov_b32_e32 v6, v202
	v_mov_b32_e32 v7, v203
	v_mov_b32_e32 v8, v204
	v_mov_b32_e32 v9, v205
	s_add_u32 s98, s42, s27
	s_addc_u32 s99, s43, 0
	s_add_u32 s98, s98, 0x80
	s_addc_u32 s99, s99, 0
	s_add_i32 s8, s11, s2
	s_cmpk_lt_u32 s8, 0x100
	s_cselect_b32 s10, s8, s11
	s_lshr_b32 s9, s10, 3
	s_and_b32 s9, s9, 0x1fffff8
	s_add_i32 s9, s9, s21
	s_and_b32 s11, s10, 7
	s_or_b32 s9, s9, s11
	v_mov_b32_e32 v0, v169
	s_lshl_b32 s9, s9, 7
	s_movk_i32 s11, 0xb00
	v_lshrrev_b32_e32 v98, 3, v0
	v_add_u32_e32 v98, s9, v98
	v_lshlrev_b32_e32 v0, 3, v0
	v_mul_lo_u32 v98, v98, s11
	s_lshl_b32 s10, s10, 4
	v_and_or_b32 v0, v0, 56, v98
	v_mov_b32_e32 v98, v169
	s_and_b32 s10, s10, 0x380
	s_cmpk_gt_u32 s8, 0xff
	s_cselect_b32 s101, 1, 0
	v_lshrrev_b32_e32 v99, 3, v98
	v_add_u32_e32 v99, s10, v99
	v_lshlrev_b32_e32 v98, 3, v98
	v_mul_lo_u32 v99, v99, s11
	v_and_or_b32 v164, v98, 56, v99
	v_add_u32_e32 v114, 0x16000, v0
	v_add_u32_e32 v124, 0x2c000, v0
	v_add_u32_e32 v136, 0x42000, v0
	v_add_u32_e32 v174, 0x16000, v164
	v_add_u32_e32 v176, 0x2c000, v164
	v_add_u32_e32 v178, 0x42000, v164
	s_setprio 1
	ds_read_b128 v[98:101], v127 offset:16384
	ds_read_b128 v[102:105], v129
	ds_read_b128 v[110:113], v127 offset:18432
	ds_read_b128 v[144:147], v127 offset:20480
	ds_read_b128 v[148:151], v127 offset:22528
	ds_read_b128 v[106:109], v129 offset:2048
	ds_read_b128 v[132:135], v129 offset:4096
	ds_read_b128 v[140:143], v129 offset:6144
	v_lshrrev_b32_e32 v14, 3, v169
	v_and_b32_e32 v15, 3, v14
	v_bfe_u32 v16, v14, 4, 1
	v_lshl_or_b32 v15, v16, 2, v15
	v_bfe_u32 v16, v14, 2, 1
	v_lshl_or_b32 v15, v16, 3, v15
	v_bfe_u32 v16, v14, 3, 1
	v_lshl_or_b32 v15, v16, 4, v15
	v_sub_u32_e32 v15, v15, v14
	v_mul_i32_i24_e32 v15, 0xb00, v15
	v_and_b32_e32 v14, 7, v14
	v_lshlrev_b32_e32 v14, 3, v14
	v_xor_b32_e32 v0, v0, v14
	v_add_u32_e32 v164, v164, v15
	v_xor_b32_e32 v164, v164, v14
	v_xor_b32_e32 v114, v114, v14
	v_add_u32_e32 v174, v174, v15
	v_xor_b32_e32 v174, v174, v14
	v_xor_b32_e32 v124, v124, v14
	v_add_u32_e32 v176, v176, v15
	v_xor_b32_e32 v176, v176, v14
	v_xor_b32_e32 v136, v136, v14
	v_add_u32_e32 v178, v178, v15
	v_xor_b32_e32 v178, v178, v14
	v_readlane_b32 s14, v254, 33
	v_readlane_b32 s15, v254, 34
	v_mov_b32_e32 v165, v1
	v_mov_b32_e32 v115, v1
	v_mov_b32_e32 v175, v1
	v_mov_b32_e32 v125, v1
	v_mov_b32_e32 v177, v1
	v_mov_b32_e32 v137, v1
	v_mov_b32_e32 v179, v1
	v_lshl_add_u64 v[180:181], v[0:1], 1, s[14:15]
	v_lshl_add_u64 v[186:187], v[164:165], 1, s[38:39]
	v_lshl_add_u64 v[114:115], v[114:115], 1, s[14:15]
	v_lshl_add_u64 v[174:175], v[174:175], 1, s[38:39]
	v_lshl_add_u64 v[188:189], v[124:125], 1, s[14:15]
	v_lshl_add_u64 v[176:177], v[176:177], 1, s[38:39]
	v_lshl_add_u64 v[136:137], v[136:137], 1, s[14:15]
	v_lshl_add_u64 v[178:179], v[178:179], 1, s[38:39]
	s_add_u32 m0, s100, 0x8000
	s_waitcnt lgkmcnt(6)
	v_mfma_f32_16x16x32_bf16 v[152:155], v[98:101], v[102:105], v[34:37]
	global_load_lds_dwordx4 v2, s[98:99]
	s_waitcnt lgkmcnt(5)
	v_mfma_f32_16x16x32_bf16 v[94:97], v[110:113], v[102:105], v[94:97]
	ds_read_b128 v[156:159], v128
	s_add_u32 m0, s100, 0xc000
	s_waitcnt lgkmcnt(5)
	v_mfma_f32_16x16x32_bf16 v[160:163], v[144:147], v[102:105], v[38:41]
	global_load_lds_dwordx4 v3, s[98:99]
	s_waitcnt lgkmcnt(4)
	v_mfma_f32_16x16x32_bf16 v[90:93], v[148:151], v[102:105], v[90:93]
	ds_read_b128 v[102:105], v128 offset:2048
	s_add_u32 m0, s100, 0x9000
	s_waitcnt lgkmcnt(4)
	v_mfma_f32_16x16x32_bf16 v[164:167], v[98:101], v[106:109], v[42:45]
	global_load_lds_dwordx4 v4, s[98:99]
	v_mfma_f32_16x16x32_bf16 v[86:89], v[110:113], v[106:109], v[86:89]
	ds_read_b128 v[194:197], v128 offset:4096
	s_add_u32 m0, s100, 0xd000
	v_mfma_f32_16x16x32_bf16 v[198:201], v[144:147], v[106:109], v[46:49]
	global_load_lds_dwordx4 v5, s[98:99]
	v_mfma_f32_16x16x32_bf16 v[82:85], v[148:151], v[106:109], v[82:85]
	ds_read_b128 v[106:109], v128 offset:6144
	s_add_u32 m0, s100, 0xa000
	s_waitcnt lgkmcnt(5)
	v_mfma_f32_16x16x32_bf16 v[202:205], v[98:101], v[132:135], v[50:53]
	global_load_lds_dwordx4 v6, s[98:99]
	v_mfma_f32_16x16x32_bf16 v[78:81], v[110:113], v[132:135], v[78:81]
	ds_read_b128 v[206:209], v130 offset:16384
	s_add_u32 m0, s100, 0xe000
	v_mfma_f32_16x16x32_bf16 v[210:213], v[144:147], v[132:135], v[54:57]
	global_load_lds_dwordx4 v7, s[98:99]
	v_mfma_f32_16x16x32_bf16 v[70:73], v[148:151], v[132:135], v[70:73]
	ds_read_b128 v[132:135], v130 offset:18432
	s_add_u32 m0, s100, 0xb000
	s_waitcnt lgkmcnt(6)
	v_mfma_f32_16x16x32_bf16 v[98:101], v[98:101], v[140:143], v[58:61]
	global_load_lds_dwordx4 v8, s[98:99]
	v_mfma_f32_16x16x32_bf16 v[66:69], v[110:113], v[140:143], v[66:69]
	ds_read_b128 v[110:113], v130 offset:20480
	s_add_u32 m0, s100, 0xf000
	v_mfma_f32_16x16x32_bf16 v[144:147], v[144:147], v[140:143], v[62:65]
	global_load_lds_dwordx4 v9, s[98:99]
	v_mfma_f32_16x16x32_bf16 v[74:77], v[148:151], v[140:143], v[74:77]
	ds_read_b128 v[140:143], v130 offset:22528
	s_waitcnt lgkmcnt(3)
	v_mfma_f32_16x16x32_bf16 v[148:151], v[206:209], v[156:159], v[152:155]
	s_waitcnt lgkmcnt(2)
	v_mfma_f32_16x16x32_bf16 v[94:97], v[132:135], v[156:159], v[94:97]
	s_waitcnt lgkmcnt(1)
	v_mfma_f32_16x16x32_bf16 v[152:155], v[110:113], v[156:159], v[160:163]
	s_waitcnt lgkmcnt(0)
	v_mfma_f32_16x16x32_bf16 v[90:93], v[140:143], v[156:159], v[90:93]
	v_mfma_f32_16x16x32_bf16 v[156:159], v[206:209], v[102:105], v[164:167]
	v_mfma_f32_16x16x32_bf16 v[86:89], v[132:135], v[102:105], v[86:89]
	v_mfma_f32_16x16x32_bf16 v[160:163], v[110:113], v[102:105], v[198:201]
	v_mfma_f32_16x16x32_bf16 v[82:85], v[140:143], v[102:105], v[82:85]
	v_mfma_f32_16x16x32_bf16 v[102:105], v[206:209], v[194:197], v[202:205]
	v_mfma_f32_16x16x32_bf16 v[78:81], v[132:135], v[194:197], v[78:81]
	v_mfma_f32_16x16x32_bf16 v[164:167], v[110:113], v[194:197], v[210:213]
	v_mfma_f32_16x16x32_bf16 v[70:73], v[140:143], v[194:197], v[70:73]
	v_mfma_f32_16x16x32_bf16 v[98:101], v[206:209], v[106:109], v[98:101]
	v_mfma_f32_16x16x32_bf16 v[66:69], v[132:135], v[106:109], v[66:69]
	v_mfma_f32_16x16x32_bf16 v[110:113], v[110:113], v[106:109], v[144:147]
	v_mfma_f32_16x16x32_bf16 v[74:77], v[140:143], v[106:109], v[74:77]
	s_waitcnt vmcnt(0)
	s_setprio 0
	s_waitcnt lgkmcnt(0)
	s_barrier
	s_setprio 1
	ds_read_b128 v[26:29], v127 offset:49152
	ds_read_b128 v[10:13], v129 offset:32768
	ds_read_b128 v[30:33], v127 offset:51200
	ds_read_b128 v[132:135], v127 offset:53248
	ds_read_b128 v[140:143], v127 offset:55296
	ds_read_b128 v[18:21], v129 offset:34816
	ds_read_b128 v[106:109], v129 offset:36864
	ds_read_b128 v[122:125], v129 offset:38912
	s_add_u32 m0, s100, 0x0
	s_waitcnt lgkmcnt(6)
	v_mfma_f32_16x16x32_bf16 v[144:147], v[26:29], v[10:13], v[148:151]
	global_load_lds_dwordx4 v[180:181], off
	s_waitcnt lgkmcnt(5)
	v_mfma_f32_16x16x32_bf16 v[94:97], v[30:33], v[10:13], v[94:97]
	ds_read_b128 v[148:151], v128 offset:32768
	s_add_u32 m0, s100, 0x4000
	s_waitcnt lgkmcnt(5)
	v_mfma_f32_16x16x32_bf16 v[152:155], v[132:135], v[10:13], v[152:155]
	global_load_lds_dwordx4 v[186:187], off
	s_waitcnt lgkmcnt(4)
	v_mfma_f32_16x16x32_bf16 v[90:93], v[140:143], v[10:13], v[90:93]
	ds_read_b128 v[194:197], v128 offset:34816
	s_add_u32 m0, s100, 0x1000
	s_waitcnt lgkmcnt(4)
	v_mfma_f32_16x16x32_bf16 v[156:159], v[26:29], v[18:21], v[156:159]
	global_load_lds_dwordx4 v[114:115], off
	v_mfma_f32_16x16x32_bf16 v[86:89], v[30:33], v[18:21], v[86:89]
	ds_read_b128 v[198:201], v128 offset:36864
	s_add_u32 m0, s100, 0x5000
	v_mfma_f32_16x16x32_bf16 v[160:163], v[132:135], v[18:21], v[160:163]
	global_load_lds_dwordx4 v[174:175], off
	v_mfma_f32_16x16x32_bf16 v[82:85], v[140:143], v[18:21], v[82:85]
	ds_read_b128 v[126:129], v128 offset:38912
	s_add_u32 m0, s100, 0x2000
	s_waitcnt lgkmcnt(5)
	v_mfma_f32_16x16x32_bf16 v[202:205], v[26:29], v[106:109], v[102:105]
	global_load_lds_dwordx4 v[188:189], off
	v_mfma_f32_16x16x32_bf16 v[78:81], v[30:33], v[106:109], v[78:81]
	ds_read_b128 v[206:209], v130 offset:49152
	s_add_u32 m0, s100, 0x6000
	v_mfma_f32_16x16x32_bf16 v[164:167], v[132:135], v[106:109], v[164:167]
	global_load_lds_dwordx4 v[176:177], off
	v_mfma_f32_16x16x32_bf16 v[70:73], v[140:143], v[106:109], v[70:73]
	ds_read_b128 v[210:213], v130 offset:51200
	s_add_u32 m0, s100, 0x3000
	s_waitcnt lgkmcnt(6)
	v_mfma_f32_16x16x32_bf16 v[214:217], v[26:29], v[122:125], v[98:101]
	global_load_lds_dwordx4 v[136:137], off
	v_mfma_f32_16x16x32_bf16 v[66:69], v[30:33], v[122:125], v[66:69]
	ds_read_b128 v[218:221], v130 offset:53248
	s_add_u32 m0, s100, 0x7000
	v_mfma_f32_16x16x32_bf16 v[110:113], v[132:135], v[122:125], v[110:113]
	global_load_lds_dwordx4 v[178:179], off
	v_mfma_f32_16x16x32_bf16 v[122:125], v[140:143], v[122:125], v[74:77]
	s_waitcnt lgkmcnt(2)
	v_mfma_f32_16x16x32_bf16 v[132:135], v[206:209], v[148:151], v[144:147]
	s_waitcnt lgkmcnt(0)
	v_mfma_f32_16x16x32_bf16 v[144:147], v[218:221], v[148:151], v[152:155]
	ds_read_b128 v[152:155], v130 offset:55296
	v_mfma_f32_16x16x32_bf16 v[140:143], v[210:213], v[148:151], v[94:97]
	s_waitcnt lgkmcnt(0)
	v_mfma_f32_16x16x32_bf16 v[148:151], v[152:155], v[148:151], v[90:93]
	v_mfma_f32_16x16x32_bf16 v[98:101], v[152:155], v[194:197], v[82:85]
	v_mfma_f32_16x16x32_bf16 v[90:93], v[210:213], v[198:201], v[78:81]
	v_mfma_f32_16x16x32_bf16 v[82:85], v[152:155], v[198:201], v[70:73]
	v_mfma_f32_16x16x32_bf16 v[78:81], v[206:209], v[126:129], v[214:217]
	v_mfma_f32_16x16x32_bf16 v[74:77], v[210:213], v[126:129], v[66:69]
	v_mfma_f32_16x16x32_bf16 v[66:69], v[218:221], v[126:129], v[110:113]
	v_mfma_f32_16x16x32_bf16 v[70:73], v[152:155], v[126:129], v[122:125]
	v_mfma_f32_16x16x32_bf16 v[156:159], v[206:209], v[194:197], v[156:159]
	v_mfma_f32_16x16x32_bf16 v[106:109], v[210:213], v[194:197], v[86:89]
	v_mfma_f32_16x16x32_bf16 v[102:105], v[218:221], v[194:197], v[160:163]
	v_mfma_f32_16x16x32_bf16 v[94:97], v[206:209], v[198:201], v[202:205]
	v_mfma_f32_16x16x32_bf16 v[86:89], v[218:221], v[198:201], v[164:167]
	s_setprio 0
	v_add_u32_e32 v110, s4, v116
	v_ashrrev_i32_e32 v111, 31, v110
	v_readlane_b32 s44, v253, 18
	v_lshlrev_b64 v[112:113], 12, v[110:111]
	v_or_b32_e32 v0, s5, v117
	v_readlane_b32 s58, v253, 32
	v_readlane_b32 s59, v253, 33
	v_lshlrev_b64 v[114:115], 2, v[0:1]
	v_lshl_add_u64 v[166:167], v[110:111], 3, s[0:1]
	v_lshl_add_u64 v[112:113], s[58:59], 0, v[112:113]
	v_lshl_add_u64 v[164:165], v[112:113], 0, v[114:115]
	s_barrier
	v_readlane_b32 s44, v253, 18
	v_readlane_b32 s45, v253, 19
	v_readlane_b32 s46, v253, 20
	v_readlane_b32 s47, v253, 21
	v_readlane_b32 s48, v253, 22
	v_readlane_b32 s49, v253, 23
	v_readlane_b32 s50, v253, 24
	v_readlane_b32 s51, v253, 25
	v_readlane_b32 s52, v253, 26
	v_readlane_b32 s53, v253, 27
	v_readlane_b32 s54, v253, 28
	v_readlane_b32 s55, v253, 29
	v_readlane_b32 s56, v253, 30
	v_readlane_b32 s57, v253, 31
	v_readlane_b32 s58, v253, 32
	v_readlane_b32 s59, v253, 33
	s_mov_b64 s[42:43], -1
	v_or_b32_e32 v0, s5, v117
	v_lshlrev_b32_e32 v0, 2, v0
	v_add_u32_e32 v110, s4, v116
	v_lshlrev_b32_e32 v50, 3, v110
	v_lshlrev_b32_e32 v110, 12, v110
	v_add_u32_e32 v110, v110, v0
	v_add_u32_e32 v111, s4, v118
	v_lshlrev_b32_e32 v54, 3, v111
	v_lshlrev_b32_e32 v111, 12, v111
	v_add_u32_e32 v111, v111, v0
	v_add_u32_e32 v112, s4, v119
	v_lshlrev_b32_e32 v58, 3, v112
	v_lshlrev_b32_e32 v112, 12, v112
	v_add_u32_e32 v112, v112, v0
	v_add_u32_e32 v113, s4, v120
	v_lshlrev_b32_e32 v62, 3, v113
	v_lshlrev_b32_e32 v113, 12, v113
	v_add_u32_e32 v113, v113, v0
	s_mov_b32 s14, 0x3fb504f3
	global_load_dwordx2 v[114:115], v50, s[0:1]
	global_load_dwordx2 v[122:123], v54, s[0:1]
	global_load_dwordx2 v[124:125], v58, s[0:1]
	global_load_dwordx2 v[126:127], v62, s[0:1]
	global_load_dwordx4 v[128:131], v0, s[34:35]
	global_load_dwordx4 v[226:229], v0, s[40:41]
	global_load_dwordx4 v[2:5], v110, s[58:59]
	global_load_dwordx4 v[6:9], v111, s[58:59]
	global_load_dwordx4 v[10:13], v112, s[58:59]
	global_load_dwordx4 v[14:17], v113, s[58:59]
	global_load_dwordx4 v[152:155], v0, s[34:35] offset:16
	global_load_dwordx4 v[230:233], v0, s[40:41] offset:16
	global_load_dwordx4 v[18:21], v110, s[58:59] offset:16
	global_load_dwordx4 v[22:25], v111, s[58:59] offset:16
	global_load_dwordx4 v[26:29], v112, s[58:59] offset:16
	global_load_dwordx4 v[30:33], v113, s[58:59] offset:16
	global_load_dwordx4 v[160:163], v0, s[34:35] offset:128
	global_load_dwordx4 v[234:237], v0, s[40:41] offset:128
	global_load_dwordx4 v[34:37], v110, s[58:59] offset:128
	global_load_dwordx4 v[38:41], v111, s[58:59] offset:128
	global_load_dwordx4 v[42:45], v112, s[58:59] offset:128
	global_load_dwordx4 v[46:49], v113, s[58:59] offset:128
	global_load_dwordx4 v[222:225], v0, s[34:35] offset:144
	global_load_dwordx4 v[238:241], v0, s[40:41] offset:144
	global_load_dwordx4 v[50:53], v110, s[58:59] offset:144
	global_load_dwordx4 v[54:57], v111, s[58:59] offset:144
	global_load_dwordx4 v[58:61], v112, s[58:59] offset:144
	global_load_dwordx4 v[62:65], v113, s[58:59] offset:144
	s_waitcnt vmcnt(21)
	v_pk_add_f32 v[2:3], v[2:3], v[114:115] op_sel_hi:[1,0] neg_lo:[0,1] neg_hi:[0,1]
	v_pk_add_f32 v[4:5], v[4:5], v[114:115] op_sel_hi:[1,0] neg_lo:[0,1] neg_hi:[0,1]
	v_pk_mul_f32 v[2:3], v[2:3], v[114:115] op_sel:[0,1]
	v_pk_mul_f32 v[4:5], v[4:5], v[114:115] op_sel:[0,1]
	v_pk_fma_f32 v[2:3], v[2:3], v[128:129], v[226:227]
	v_pk_fma_f32 v[4:5], v[4:5], v[130:131], v[228:229]
	v_pk_fma_f32 v[132:133], v[2:3], s[14:15], v[132:133] op_sel_hi:[1,0,1]
	v_pk_fma_f32 v[134:135], v[4:5], s[14:15], v[134:135] op_sel_hi:[1,0,1]
	global_store_dwordx4 v110, v[132:135], s[58:59]
	s_waitcnt vmcnt(21)
	v_pk_add_f32 v[6:7], v[6:7], v[122:123] op_sel_hi:[1,0] neg_lo:[0,1] neg_hi:[0,1]
	v_pk_add_f32 v[8:9], v[8:9], v[122:123] op_sel_hi:[1,0] neg_lo:[0,1] neg_hi:[0,1]
	v_pk_mul_f32 v[6:7], v[6:7], v[122:123] op_sel:[0,1]
	v_pk_mul_f32 v[8:9], v[8:9], v[122:123] op_sel:[0,1]
	v_pk_fma_f32 v[6:7], v[6:7], v[128:129], v[226:227]
	v_pk_fma_f32 v[8:9], v[8:9], v[130:131], v[228:229]
	v_pk_fma_f32 v[156:157], v[6:7], s[14:15], v[156:157] op_sel_hi:[1,0,1]
	v_pk_fma_f32 v[158:159], v[8:9], s[14:15], v[158:159] op_sel_hi:[1,0,1]
	global_store_dwordx4 v111, v[156:159], s[58:59]
	s_waitcnt vmcnt(21)
	v_pk_add_f32 v[10:11], v[10:11], v[124:125] op_sel_hi:[1,0] neg_lo:[0,1] neg_hi:[0,1]
	v_pk_add_f32 v[12:13], v[12:13], v[124:125] op_sel_hi:[1,0] neg_lo:[0,1] neg_hi:[0,1]
	v_pk_mul_f32 v[10:11], v[10:11], v[124:125] op_sel:[0,1]
	v_pk_mul_f32 v[12:13], v[12:13], v[124:125] op_sel:[0,1]
	v_pk_fma_f32 v[10:11], v[10:11], v[128:129], v[226:227]
	v_pk_fma_f32 v[12:13], v[12:13], v[130:131], v[228:229]
	v_pk_fma_f32 v[94:95], v[10:11], s[14:15], v[94:95] op_sel_hi:[1,0,1]
	v_pk_fma_f32 v[96:97], v[12:13], s[14:15], v[96:97] op_sel_hi:[1,0,1]
	global_store_dwordx4 v112, v[94:97], s[58:59]
	s_waitcnt vmcnt(21)
	v_pk_add_f32 v[14:15], v[14:15], v[126:127] op_sel_hi:[1,0] neg_lo:[0,1] neg_hi:[0,1]
	v_pk_add_f32 v[16:17], v[16:17], v[126:127] op_sel_hi:[1,0] neg_lo:[0,1] neg_hi:[0,1]
	v_pk_mul_f32 v[14:15], v[14:15], v[126:127] op_sel:[0,1]
	v_pk_mul_f32 v[16:17], v[16:17], v[126:127] op_sel:[0,1]
	v_pk_fma_f32 v[14:15], v[14:15], v[128:129], v[226:227]
	v_pk_fma_f32 v[16:17], v[16:17], v[130:131], v[228:229]
	v_pk_fma_f32 v[78:79], v[14:15], s[14:15], v[78:79] op_sel_hi:[1,0,1]
	v_pk_fma_f32 v[80:81], v[16:17], s[14:15], v[80:81] op_sel_hi:[1,0,1]
	global_store_dwordx4 v113, v[78:81], s[58:59]
	s_waitcnt vmcnt(19)
	v_pk_add_f32 v[18:19], v[18:19], v[114:115] op_sel_hi:[1,0] neg_lo:[0,1] neg_hi:[0,1]
	v_pk_add_f32 v[20:21], v[20:21], v[114:115] op_sel_hi:[1,0] neg_lo:[0,1] neg_hi:[0,1]
	v_pk_mul_f32 v[18:19], v[18:19], v[114:115] op_sel:[0,1]
	v_pk_mul_f32 v[20:21], v[20:21], v[114:115] op_sel:[0,1]
	v_pk_fma_f32 v[18:19], v[18:19], v[152:153], v[230:231]
	v_pk_fma_f32 v[20:21], v[20:21], v[154:155], v[232:233]
	v_pk_fma_f32 v[140:141], v[18:19], s[14:15], v[140:141] op_sel_hi:[1,0,1]
	v_pk_fma_f32 v[142:143], v[20:21], s[14:15], v[142:143] op_sel_hi:[1,0,1]
	global_store_dwordx4 v110, v[140:143], s[58:59] offset:16
	s_waitcnt vmcnt(19)
	v_pk_add_f32 v[22:23], v[22:23], v[122:123] op_sel_hi:[1,0] neg_lo:[0,1] neg_hi:[0,1]
	v_pk_add_f32 v[24:25], v[24:25], v[122:123] op_sel_hi:[1,0] neg_lo:[0,1] neg_hi:[0,1]
	v_pk_mul_f32 v[22:23], v[22:23], v[122:123] op_sel:[0,1]
	v_pk_mul_f32 v[24:25], v[24:25], v[122:123] op_sel:[0,1]
	v_pk_fma_f32 v[22:23], v[22:23], v[152:153], v[230:231]
	v_pk_fma_f32 v[24:25], v[24:25], v[154:155], v[232:233]
	v_pk_fma_f32 v[106:107], v[22:23], s[14:15], v[106:107] op_sel_hi:[1,0,1]
	v_pk_fma_f32 v[108:109], v[24:25], s[14:15], v[108:109] op_sel_hi:[1,0,1]
	global_store_dwordx4 v111, v[106:109], s[58:59] offset:16
	s_waitcnt vmcnt(19)
	v_pk_add_f32 v[26:27], v[26:27], v[124:125] op_sel_hi:[1,0] neg_lo:[0,1] neg_hi:[0,1]
	v_pk_add_f32 v[28:29], v[28:29], v[124:125] op_sel_hi:[1,0] neg_lo:[0,1] neg_hi:[0,1]
	v_pk_mul_f32 v[26:27], v[26:27], v[124:125] op_sel:[0,1]
	v_pk_mul_f32 v[28:29], v[28:29], v[124:125] op_sel:[0,1]
	v_pk_fma_f32 v[26:27], v[26:27], v[152:153], v[230:231]
	v_pk_fma_f32 v[28:29], v[28:29], v[154:155], v[232:233]
	v_pk_fma_f32 v[90:91], v[26:27], s[14:15], v[90:91] op_sel_hi:[1,0,1]
	v_pk_fma_f32 v[92:93], v[28:29], s[14:15], v[92:93] op_sel_hi:[1,0,1]
	global_store_dwordx4 v112, v[90:93], s[58:59] offset:16
	s_waitcnt vmcnt(19)
	v_pk_add_f32 v[30:31], v[30:31], v[126:127] op_sel_hi:[1,0] neg_lo:[0,1] neg_hi:[0,1]
	v_pk_add_f32 v[32:33], v[32:33], v[126:127] op_sel_hi:[1,0] neg_lo:[0,1] neg_hi:[0,1]
	v_pk_mul_f32 v[30:31], v[30:31], v[126:127] op_sel:[0,1]
	v_pk_mul_f32 v[32:33], v[32:33], v[126:127] op_sel:[0,1]
	v_pk_fma_f32 v[30:31], v[30:31], v[152:153], v[230:231]
	v_pk_fma_f32 v[32:33], v[32:33], v[154:155], v[232:233]
	v_pk_fma_f32 v[74:75], v[30:31], s[14:15], v[74:75] op_sel_hi:[1,0,1]
	v_pk_fma_f32 v[76:77], v[32:33], s[14:15], v[76:77] op_sel_hi:[1,0,1]
	global_store_dwordx4 v113, v[74:77], s[58:59] offset:16
	s_waitcnt vmcnt(17)
	v_pk_add_f32 v[34:35], v[34:35], v[114:115] op_sel_hi:[1,0] neg_lo:[0,1] neg_hi:[0,1]
	v_pk_add_f32 v[36:37], v[36:37], v[114:115] op_sel_hi:[1,0] neg_lo:[0,1] neg_hi:[0,1]
	v_pk_mul_f32 v[34:35], v[34:35], v[114:115] op_sel:[0,1]
	v_pk_mul_f32 v[36:37], v[36:37], v[114:115] op_sel:[0,1]
	v_pk_fma_f32 v[34:35], v[34:35], v[160:161], v[234:235]
	v_pk_fma_f32 v[36:37], v[36:37], v[162:163], v[236:237]
	v_pk_fma_f32 v[144:145], v[34:35], s[14:15], v[144:145] op_sel_hi:[1,0,1]
	v_pk_fma_f32 v[146:147], v[36:37], s[14:15], v[146:147] op_sel_hi:[1,0,1]
	global_store_dwordx4 v110, v[144:147], s[58:59] offset:128
	s_waitcnt vmcnt(17)
	v_pk_add_f32 v[38:39], v[38:39], v[122:123] op_sel_hi:[1,0] neg_lo:[0,1] neg_hi:[0,1]
	v_pk_add_f32 v[40:41], v[40:41], v[122:123] op_sel_hi:[1,0] neg_lo:[0,1] neg_hi:[0,1]
	v_pk_mul_f32 v[38:39], v[38:39], v[122:123] op_sel:[0,1]
	v_pk_mul_f32 v[40:41], v[40:41], v[122:123] op_sel:[0,1]
	v_pk_fma_f32 v[38:39], v[38:39], v[160:161], v[234:235]
	v_pk_fma_f32 v[40:41], v[40:41], v[162:163], v[236:237]
	v_pk_fma_f32 v[102:103], v[38:39], s[14:15], v[102:103] op_sel_hi:[1,0,1]
	v_pk_fma_f32 v[104:105], v[40:41], s[14:15], v[104:105] op_sel_hi:[1,0,1]
	global_store_dwordx4 v111, v[102:105], s[58:59] offset:128
	s_waitcnt vmcnt(17)
	v_pk_add_f32 v[42:43], v[42:43], v[124:125] op_sel_hi:[1,0] neg_lo:[0,1] neg_hi:[0,1]
	v_pk_add_f32 v[44:45], v[44:45], v[124:125] op_sel_hi:[1,0] neg_lo:[0,1] neg_hi:[0,1]
	v_pk_mul_f32 v[42:43], v[42:43], v[124:125] op_sel:[0,1]
	v_pk_mul_f32 v[44:45], v[44:45], v[124:125] op_sel:[0,1]
	v_pk_fma_f32 v[42:43], v[42:43], v[160:161], v[234:235]
	v_pk_fma_f32 v[44:45], v[44:45], v[162:163], v[236:237]
	v_pk_fma_f32 v[86:87], v[42:43], s[14:15], v[86:87] op_sel_hi:[1,0,1]
	v_pk_fma_f32 v[88:89], v[44:45], s[14:15], v[88:89] op_sel_hi:[1,0,1]
	global_store_dwordx4 v112, v[86:89], s[58:59] offset:128
	s_waitcnt vmcnt(17)
	v_pk_add_f32 v[46:47], v[46:47], v[126:127] op_sel_hi:[1,0] neg_lo:[0,1] neg_hi:[0,1]
	v_pk_add_f32 v[48:49], v[48:49], v[126:127] op_sel_hi:[1,0] neg_lo:[0,1] neg_hi:[0,1]
	v_pk_mul_f32 v[46:47], v[46:47], v[126:127] op_sel:[0,1]
	v_pk_mul_f32 v[48:49], v[48:49], v[126:127] op_sel:[0,1]
	v_pk_fma_f32 v[46:47], v[46:47], v[160:161], v[234:235]
	v_pk_fma_f32 v[48:49], v[48:49], v[162:163], v[236:237]
	v_pk_fma_f32 v[66:67], v[46:47], s[14:15], v[66:67] op_sel_hi:[1,0,1]
	v_pk_fma_f32 v[68:69], v[48:49], s[14:15], v[68:69] op_sel_hi:[1,0,1]
	global_store_dwordx4 v113, v[66:69], s[58:59] offset:128
	s_waitcnt vmcnt(15)
	v_pk_add_f32 v[50:51], v[50:51], v[114:115] op_sel_hi:[1,0] neg_lo:[0,1] neg_hi:[0,1]
	v_pk_add_f32 v[52:53], v[52:53], v[114:115] op_sel_hi:[1,0] neg_lo:[0,1] neg_hi:[0,1]
	v_pk_mul_f32 v[50:51], v[50:51], v[114:115] op_sel:[0,1]
	v_pk_mul_f32 v[52:53], v[52:53], v[114:115] op_sel:[0,1]
	v_pk_fma_f32 v[50:51], v[50:51], v[222:223], v[238:239]
	v_pk_fma_f32 v[52:53], v[52:53], v[224:225], v[240:241]
	v_pk_fma_f32 v[148:149], v[50:51], s[14:15], v[148:149] op_sel_hi:[1,0,1]
	v_pk_fma_f32 v[150:151], v[52:53], s[14:15], v[150:151] op_sel_hi:[1,0,1]
	global_store_dwordx4 v110, v[148:151], s[58:59] offset:144
	s_waitcnt vmcnt(15)
	v_pk_add_f32 v[54:55], v[54:55], v[122:123] op_sel_hi:[1,0] neg_lo:[0,1] neg_hi:[0,1]
	v_pk_add_f32 v[56:57], v[56:57], v[122:123] op_sel_hi:[1,0] neg_lo:[0,1] neg_hi:[0,1]
	v_pk_mul_f32 v[54:55], v[54:55], v[122:123] op_sel:[0,1]
	v_pk_mul_f32 v[56:57], v[56:57], v[122:123] op_sel:[0,1]
	v_pk_fma_f32 v[54:55], v[54:55], v[222:223], v[238:239]
	v_pk_fma_f32 v[56:57], v[56:57], v[224:225], v[240:241]
	v_pk_fma_f32 v[98:99], v[54:55], s[14:15], v[98:99] op_sel_hi:[1,0,1]
	v_pk_fma_f32 v[100:101], v[56:57], s[14:15], v[100:101] op_sel_hi:[1,0,1]
	global_store_dwordx4 v111, v[98:101], s[58:59] offset:144
	s_waitcnt vmcnt(15)
	v_pk_add_f32 v[58:59], v[58:59], v[124:125] op_sel_hi:[1,0] neg_lo:[0,1] neg_hi:[0,1]
	v_pk_add_f32 v[60:61], v[60:61], v[124:125] op_sel_hi:[1,0] neg_lo:[0,1] neg_hi:[0,1]
	v_pk_mul_f32 v[58:59], v[58:59], v[124:125] op_sel:[0,1]
	v_pk_mul_f32 v[60:61], v[60:61], v[124:125] op_sel:[0,1]
	v_pk_fma_f32 v[58:59], v[58:59], v[222:223], v[238:239]
	v_pk_fma_f32 v[60:61], v[60:61], v[224:225], v[240:241]
	v_pk_fma_f32 v[82:83], v[58:59], s[14:15], v[82:83] op_sel_hi:[1,0,1]
	v_pk_fma_f32 v[84:85], v[60:61], s[14:15], v[84:85] op_sel_hi:[1,0,1]
	global_store_dwordx4 v112, v[82:85], s[58:59] offset:144
	s_waitcnt vmcnt(15)
	v_pk_add_f32 v[62:63], v[62:63], v[126:127] op_sel_hi:[1,0] neg_lo:[0,1] neg_hi:[0,1]
	v_pk_add_f32 v[64:65], v[64:65], v[126:127] op_sel_hi:[1,0] neg_lo:[0,1] neg_hi:[0,1]
	v_pk_mul_f32 v[62:63], v[62:63], v[126:127] op_sel:[0,1]
	v_pk_mul_f32 v[64:65], v[64:65], v[126:127] op_sel:[0,1]
	v_pk_fma_f32 v[62:63], v[62:63], v[222:223], v[238:239]
	v_pk_fma_f32 v[64:65], v[64:65], v[224:225], v[240:241]
	v_pk_fma_f32 v[70:71], v[62:63], s[14:15], v[70:71] op_sel_hi:[1,0,1]
	v_pk_fma_f32 v[72:73], v[64:65], s[14:15], v[72:73] op_sel_hi:[1,0,1]
	global_store_dwordx4 v113, v[70:73], s[58:59] offset:144
	s_cmp_lg_u32 s101, 0
	s_cbranch_scc1 .LBB0_126
	v_mov_b32_e32 v0, v169
	v_mov_b32_e32 v67, v169
	s_movk_i32 s4, 0xb00
	v_lshrrev_b32_e32 v66, 3, v0
	v_lshrrev_b32_e32 v69, 3, v67
	v_add_u32_e32 v66, s9, v66
	v_add_u32_e32 v69, s10, v69
	v_lshlrev_b32_e32 v0, 3, v0
	v_mul_lo_u32 v66, v66, s4
	v_lshlrev_b32_e32 v67, 3, v67
	v_mul_lo_u32 v69, v69, s4
	v_and_or_b32 v0, v0, 56, v66
	v_and_or_b32 v72, v67, 56, v69
	v_add_u32_e32 v66, 0x16000, v0
	v_add_u32_e32 v68, 0x2c000, v0
	v_add_u32_e32 v70, 0x42000, v0
	v_add_u32_e32 v74, 0x16000, v72
	v_add_u32_e32 v76, 0x2c000, v72
	v_add_u32_e32 v78, 0x42000, v72
	s_mov_b64 s[42:43], 0
	s_branch .LBB0_126

.LBB0_157:
	s_setprio 1
	s_add_u32 s98, s38, s36
	s_addc_u32 s99, s39, 0
	s_add_u32 s98, s98, 0x80
	s_addc_u32 s99, s99, 0
	v_add_u32_e32 v122, v119, v118
	v_add_u32_e32 v124, v119, v120
	v_add_u32_e32 v123, v121, v120
	ds_read_b128 v[126:129], v122 offset:16384
	ds_read_b128 v[130:133], v124
	ds_read_b128 v[144:147], v122 offset:18432
	ds_read_b128 v[158:161], v122 offset:20480
	ds_read_b128 v[162:165], v122 offset:22528
	ds_read_b128 v[134:137], v124 offset:2048
	ds_read_b128 v[140:143], v124 offset:4096
	ds_read_b128 v[148:151], v124 offset:6144
	s_add_u32 m0, s100, 0x8000
	s_waitcnt lgkmcnt(6)
	v_mfma_f32_16x16x32_bf16 v[34:37], v[126:129], v[130:133], v[34:37]
	global_load_lds_dwordx4 v194, s[98:99]
	s_waitcnt lgkmcnt(5)
	v_mfma_f32_16x16x32_bf16 v[94:97], v[144:147], v[130:133], v[94:97]
	ds_read_b128 v[198:201], v123
	s_add_u32 m0, s100, 0xc000
	s_waitcnt lgkmcnt(5)
	v_mfma_f32_16x16x32_bf16 v[38:41], v[158:161], v[130:133], v[38:41]
	global_load_lds_dwordx4 v195, s[98:99]
	s_waitcnt lgkmcnt(4)
	v_mfma_f32_16x16x32_bf16 v[90:93], v[162:165], v[130:133], v[90:93]
	ds_read_b128 v[206:209], v123 offset:2048
	s_add_u32 m0, s100, 0x9000
	s_waitcnt lgkmcnt(4)
	v_mfma_f32_16x16x32_bf16 v[42:45], v[126:129], v[134:137], v[42:45]
	global_load_lds_dwordx4 v196, s[98:99]
	v_mfma_f32_16x16x32_bf16 v[86:89], v[144:147], v[134:137], v[86:89]
	ds_read_b128 v[214:217], v123 offset:4096
	s_add_u32 m0, s100, 0xd000
	v_mfma_f32_16x16x32_bf16 v[46:49], v[158:161], v[134:137], v[46:49]
	global_load_lds_dwordx4 v197, s[98:99]
	v_mfma_f32_16x16x32_bf16 v[82:85], v[162:165], v[134:137], v[82:85]
	v_add_u32_e32 v130, v121, v118
	ds_read_b128 v[132:135], v123 offset:6144
	s_add_u32 m0, s100, 0xa000
	s_waitcnt lgkmcnt(5)
	v_mfma_f32_16x16x32_bf16 v[50:53], v[126:129], v[140:143], v[50:53]
	global_load_lds_dwordx4 v202, s[98:99]
	v_mfma_f32_16x16x32_bf16 v[78:81], v[144:147], v[140:143], v[78:81]
	ds_read_b128 v[226:229], v130 offset:16384
	s_add_u32 m0, s100, 0xe000
	v_mfma_f32_16x16x32_bf16 v[54:57], v[158:161], v[140:143], v[54:57]
	global_load_lds_dwordx4 v203, s[98:99]
	v_mfma_f32_16x16x32_bf16 v[70:73], v[162:165], v[140:143], v[70:73]
	ds_read_b128 v[140:143], v130 offset:18432
	s_add_u32 m0, s100, 0xb000
	s_waitcnt lgkmcnt(6)
	v_mfma_f32_16x16x32_bf16 v[58:61], v[126:129], v[148:151], v[58:61]
	global_load_lds_dwordx4 v204, s[98:99]
	v_mfma_f32_16x16x32_bf16 v[66:69], v[144:147], v[148:151], v[66:69]
	ds_read_b128 v[144:147], v130 offset:20480
	s_add_u32 m0, s100, 0xf000
	v_mfma_f32_16x16x32_bf16 v[62:65], v[158:161], v[148:151], v[62:65]
	global_load_lds_dwordx4 v205, s[98:99]
	v_mfma_f32_16x16x32_bf16 v[74:77], v[162:165], v[148:151], v[74:77]
	ds_read_b128 v[148:151], v130 offset:22528
	s_waitcnt lgkmcnt(3)
	v_mfma_f32_16x16x32_bf16 v[34:37], v[226:229], v[198:201], v[34:37]
	s_waitcnt lgkmcnt(2)
	v_mfma_f32_16x16x32_bf16 v[94:97], v[140:143], v[198:201], v[94:97]
	s_waitcnt lgkmcnt(1)
	v_mfma_f32_16x16x32_bf16 v[38:41], v[144:147], v[198:201], v[38:41]
	s_waitcnt lgkmcnt(0)
	v_mfma_f32_16x16x32_bf16 v[90:93], v[148:151], v[198:201], v[90:93]
	v_mfma_f32_16x16x32_bf16 v[42:45], v[226:229], v[206:209], v[42:45]
	v_mfma_f32_16x16x32_bf16 v[86:89], v[140:143], v[206:209], v[86:89]
	v_mfma_f32_16x16x32_bf16 v[46:49], v[144:147], v[206:209], v[46:49]
	v_mfma_f32_16x16x32_bf16 v[82:85], v[148:151], v[206:209], v[82:85]
	v_mfma_f32_16x16x32_bf16 v[50:53], v[226:229], v[214:217], v[50:53]
	v_mfma_f32_16x16x32_bf16 v[78:81], v[140:143], v[214:217], v[78:81]
	v_mfma_f32_16x16x32_bf16 v[54:57], v[144:147], v[214:217], v[54:57]
	v_mfma_f32_16x16x32_bf16 v[70:73], v[148:151], v[214:217], v[70:73]
	v_mfma_f32_16x16x32_bf16 v[58:61], v[226:229], v[132:135], v[58:61]
	v_mfma_f32_16x16x32_bf16 v[66:69], v[140:143], v[132:135], v[66:69]
	v_mfma_f32_16x16x32_bf16 v[62:65], v[144:147], v[132:135], v[62:65]
	v_mfma_f32_16x16x32_bf16 v[74:77], v[148:151], v[132:135], v[74:77]
	s_waitcnt vmcnt(0)
	s_setprio 0
	s_waitcnt lgkmcnt(0)
	s_barrier
	s_setprio 1
	s_add_u32 s98, s98, 0x80
	s_addc_u32 s99, s99, 0
	ds_read_b128 v[26:29], v122 offset:49152
	ds_read_b128 v[10:13], v124 offset:32768
	ds_read_b128 v[30:33], v122 offset:51200
	ds_read_b128 v[144:147], v122 offset:53248
	ds_read_b128 v[148:151], v122 offset:55296
	ds_read_b128 v[18:21], v124 offset:34816
	ds_read_b128 v[132:135], v124 offset:36864
	ds_read_b128 v[140:143], v124 offset:38912
	s_add_u32 m0, s100, 0x0
	s_waitcnt lgkmcnt(6)
	v_mfma_f32_16x16x32_bf16 v[34:37], v[26:29], v[10:13], v[34:37]
	global_load_lds_dwordx4 v194, s[98:99]
	s_waitcnt lgkmcnt(5)
	v_mfma_f32_16x16x32_bf16 v[94:97], v[30:33], v[10:13], v[94:97]
	ds_read_b128 v[162:165], v123 offset:32768
	s_add_u32 m0, s100, 0x4000
	s_waitcnt lgkmcnt(5)
	v_mfma_f32_16x16x32_bf16 v[38:41], v[144:147], v[10:13], v[38:41]
	global_load_lds_dwordx4 v195, s[98:99]
	s_waitcnt lgkmcnt(4)
	v_mfma_f32_16x16x32_bf16 v[90:93], v[148:151], v[10:13], v[90:93]
	ds_read_b128 v[198:201], v123 offset:34816
	s_add_u32 m0, s100, 0x1000
	s_waitcnt lgkmcnt(4)
	v_mfma_f32_16x16x32_bf16 v[42:45], v[26:29], v[18:21], v[42:45]
	global_load_lds_dwordx4 v196, s[98:99]
	v_mfma_f32_16x16x32_bf16 v[86:89], v[30:33], v[18:21], v[86:89]
	ds_read_b128 v[206:209], v123 offset:36864
	s_add_u32 m0, s100, 0x5000
	v_mfma_f32_16x16x32_bf16 v[46:49], v[144:147], v[18:21], v[46:49]
	global_load_lds_dwordx4 v197, s[98:99]
	v_mfma_f32_16x16x32_bf16 v[82:85], v[148:151], v[18:21], v[82:85]
	ds_read_b128 v[214:217], v123 offset:38912
	s_add_u32 m0, s100, 0x2000
	s_waitcnt lgkmcnt(5)
	v_mfma_f32_16x16x32_bf16 v[50:53], v[26:29], v[132:135], v[50:53]
	global_load_lds_dwordx4 v202, s[98:99]
	v_mfma_f32_16x16x32_bf16 v[78:81], v[30:33], v[132:135], v[78:81]
	ds_read_b128 v[226:229], v130 offset:49152
	s_add_u32 m0, s100, 0x6000
	v_mfma_f32_16x16x32_bf16 v[54:57], v[144:147], v[132:135], v[54:57]
	global_load_lds_dwordx4 v203, s[98:99]
	v_mfma_f32_16x16x32_bf16 v[70:73], v[148:151], v[132:135], v[70:73]
	ds_read_b128 v[132:135], v130 offset:51200
	s_add_u32 m0, s100, 0x3000
	s_waitcnt lgkmcnt(6)
	v_mfma_f32_16x16x32_bf16 v[58:61], v[26:29], v[140:143], v[58:61]
	global_load_lds_dwordx4 v204, s[98:99]
	v_mfma_f32_16x16x32_bf16 v[66:69], v[30:33], v[140:143], v[66:69]
	ds_read_b128 v[234:237], v130 offset:53248
	s_add_u32 m0, s100, 0x7000
	v_mfma_f32_16x16x32_bf16 v[62:65], v[144:147], v[140:143], v[62:65]
	global_load_lds_dwordx4 v205, s[98:99]
	v_mfma_f32_16x16x32_bf16 v[74:77], v[148:151], v[140:143], v[74:77]
	ds_read_b128 v[140:143], v130 offset:55296
	s_waitcnt lgkmcnt(3)
	v_mfma_f32_16x16x32_bf16 v[34:37], v[226:229], v[162:165], v[34:37]
	s_waitcnt lgkmcnt(2)
	v_mfma_f32_16x16x32_bf16 v[94:97], v[132:135], v[162:165], v[94:97]
	s_waitcnt lgkmcnt(1)
	v_mfma_f32_16x16x32_bf16 v[38:41], v[234:237], v[162:165], v[38:41]
	s_waitcnt lgkmcnt(0)
	v_mfma_f32_16x16x32_bf16 v[90:93], v[140:143], v[162:165], v[90:93]
	v_mfma_f32_16x16x32_bf16 v[42:45], v[226:229], v[198:201], v[42:45]
	v_mfma_f32_16x16x32_bf16 v[86:89], v[132:135], v[198:201], v[86:89]
	v_mfma_f32_16x16x32_bf16 v[46:49], v[234:237], v[198:201], v[46:49]
	v_mfma_f32_16x16x32_bf16 v[82:85], v[140:143], v[198:201], v[82:85]
	v_mfma_f32_16x16x32_bf16 v[50:53], v[226:229], v[206:209], v[50:53]
	v_mfma_f32_16x16x32_bf16 v[78:81], v[132:135], v[206:209], v[78:81]
	v_mfma_f32_16x16x32_bf16 v[54:57], v[234:237], v[206:209], v[54:57]
	v_mfma_f32_16x16x32_bf16 v[70:73], v[140:143], v[206:209], v[70:73]
	v_mfma_f32_16x16x32_bf16 v[58:61], v[226:229], v[214:217], v[58:61]
	v_mfma_f32_16x16x32_bf16 v[66:69], v[132:135], v[214:217], v[66:69]
	v_mfma_f32_16x16x32_bf16 v[62:65], v[234:237], v[214:217], v[62:65]
	v_mfma_f32_16x16x32_bf16 v[74:77], v[140:143], v[214:217], v[74:77]
	s_waitcnt vmcnt(0)
	s_setprio 0
	s_add_i32 s5, s5, 2
	s_add_u32 s38, s38, 0x100
	s_addc_u32 s39, s39, 0
	s_cmp_lt_u32 s5, 12
	s_waitcnt lgkmcnt(0)
	s_barrier
	s_cbranch_scc1 .LBB0_157
	v_mov_b32_e32 v2, v194
	v_mov_b32_e32 v3, v195
	v_mov_b32_e32 v4, v196
	v_mov_b32_e32 v5, v197
	v_mov_b32_e32 v6, v202
	v_mov_b32_e32 v7, v203
	v_mov_b32_e32 v8, v204
	v_mov_b32_e32 v9, v205
	s_add_u32 s98, s38, s36
	s_addc_u32 s99, s39, 0
	s_add_u32 s98, s98, 0x80
	s_addc_u32 s99, s99, 0
	s_add_i32 s5, s11, s2
	s_cmpk_lt_u32 s5, 0x100
	s_cselect_b64 s[44:45], -1, 0
	s_and_b64 s[8:9], s[44:45], exec
	s_cselect_b32 s9, s5, s11
	s_lshr_b32 s8, s9, 3
	s_and_b32 s8, s8, 0x1fffff8
	s_add_i32 s8, s8, s21
	s_and_b32 s11, s9, 7
	v_mov_b32_e32 v0, v169
	s_or_b32 s8, s8, s11
	s_lshl_b32 s8, s8, 7
	v_lshrrev_b32_e32 v98, 3, v0
	v_lshlrev_b32_e32 v0, 3, v0
	v_add_u32_e32 v98, s8, v98
	v_and_b32_e32 v0, 56, v0
	v_lshl_or_b32 v0, v98, 10, v0
	v_mov_b32_e32 v98, v169
	s_lshl_b32 s9, s9, 4
	s_and_b32 s9, s9, 0x380
	v_lshrrev_b32_e32 v99, 3, v98
	v_lshlrev_b32_e32 v98, 3, v98
	v_add_u32_e32 v99, s9, v99
	v_and_b32_e32 v98, 56, v98
	v_add_u32_e32 v114, 0x8000, v0
	v_add_u32_e32 v136, 0x10000, v0
	v_lshl_or_b32 v162, v99, 10, v98
	v_add_u32_e32 v166, 0x18000, v0
	v_add_u32_e32 v174, 0x8000, v162
	v_add_u32_e32 v176, 0x10000, v162
	v_add_u32_e32 v178, 0x18000, v162
	s_setprio 1
	ds_read_b128 v[98:101], v122 offset:16384
	ds_read_b128 v[102:105], v124
	ds_read_b128 v[110:113], v122 offset:18432
	ds_read_b128 v[132:135], v122 offset:20480
	ds_read_b128 v[140:143], v122 offset:22528
	ds_read_b128 v[106:109], v124 offset:2048
	ds_read_b128 v[118:121], v124 offset:4096
	ds_read_b128 v[126:129], v124 offset:6144
	v_lshrrev_b32_e32 v14, 3, v169
	v_and_b32_e32 v15, 3, v14
	v_bfe_u32 v16, v14, 4, 1
	v_lshl_or_b32 v15, v16, 2, v15
	v_bfe_u32 v16, v14, 2, 1
	v_lshl_or_b32 v15, v16, 3, v15
	v_bfe_u32 v16, v14, 3, 1
	v_lshl_or_b32 v15, v16, 4, v15
	v_sub_u32_e32 v15, v15, v14
	v_mul_i32_i24_e32 v15, 0x400, v15
	v_and_b32_e32 v14, 7, v14
	v_lshlrev_b32_e32 v14, 3, v14
	v_xor_b32_e32 v0, v0, v14
	v_add_u32_e32 v162, v162, v15
	v_xor_b32_e32 v162, v162, v14
	v_xor_b32_e32 v114, v114, v14
	v_add_u32_e32 v174, v174, v15
	v_xor_b32_e32 v174, v174, v14
	v_xor_b32_e32 v136, v136, v14
	v_add_u32_e32 v176, v176, v15
	v_xor_b32_e32 v176, v176, v14
	v_xor_b32_e32 v166, v166, v14
	v_add_u32_e32 v178, v178, v15
	v_xor_b32_e32 v178, v178, v14
	v_readlane_b32 s14, v254, 45
	v_readlane_b32 s15, v254, 46
	v_mov_b32_e32 v163, v1
	v_mov_b32_e32 v115, v1
	v_mov_b32_e32 v175, v1
	v_mov_b32_e32 v137, v1
	v_mov_b32_e32 v177, v1
	v_mov_b32_e32 v167, v1
	v_mov_b32_e32 v179, v1
	v_lshl_add_u64 v[180:181], v[0:1], 1, s[14:15]
	v_lshl_add_u64 v[186:187], v[162:163], 1, s[34:35]
	v_lshl_add_u64 v[188:189], v[114:115], 1, s[14:15]
	v_lshl_add_u64 v[174:175], v[174:175], 1, s[34:35]
	v_lshl_add_u64 v[136:137], v[136:137], 1, s[14:15]
	v_lshl_add_u64 v[176:177], v[176:177], 1, s[34:35]
	v_lshl_add_u64 v[166:167], v[166:167], 1, s[14:15]
	v_lshl_add_u64 v[178:179], v[178:179], 1, s[34:35]
	s_add_u32 m0, s100, 0x8000
	s_waitcnt lgkmcnt(6)
	v_mfma_f32_16x16x32_bf16 v[144:147], v[98:101], v[102:105], v[34:37]
	global_load_lds_dwordx4 v2, s[98:99]
	s_waitcnt lgkmcnt(5)
	v_mfma_f32_16x16x32_bf16 v[94:97], v[110:113], v[102:105], v[94:97]
	ds_read_b128 v[148:151], v123
	s_add_u32 m0, s100, 0xc000
	s_waitcnt lgkmcnt(5)
	v_mfma_f32_16x16x32_bf16 v[158:161], v[132:135], v[102:105], v[38:41]
	global_load_lds_dwordx4 v3, s[98:99]
	s_waitcnt lgkmcnt(4)
	v_mfma_f32_16x16x32_bf16 v[90:93], v[140:143], v[102:105], v[90:93]
	ds_read_b128 v[102:105], v123 offset:2048
	s_add_u32 m0, s100, 0x9000
	s_waitcnt lgkmcnt(4)
	v_mfma_f32_16x16x32_bf16 v[162:165], v[98:101], v[106:109], v[42:45]
	global_load_lds_dwordx4 v4, s[98:99]
	v_mfma_f32_16x16x32_bf16 v[86:89], v[110:113], v[106:109], v[86:89]
	ds_read_b128 v[194:197], v123 offset:4096
	s_add_u32 m0, s100, 0xd000
	v_mfma_f32_16x16x32_bf16 v[198:201], v[132:135], v[106:109], v[46:49]
	global_load_lds_dwordx4 v5, s[98:99]
	v_mfma_f32_16x16x32_bf16 v[82:85], v[140:143], v[106:109], v[82:85]
	ds_read_b128 v[106:109], v123 offset:6144
	s_add_u32 m0, s100, 0xa000
	s_waitcnt lgkmcnt(5)
	v_mfma_f32_16x16x32_bf16 v[202:205], v[98:101], v[118:121], v[50:53]
	global_load_lds_dwordx4 v6, s[98:99]
	v_mfma_f32_16x16x32_bf16 v[78:81], v[110:113], v[118:121], v[78:81]
	ds_read_b128 v[206:209], v130 offset:16384
	s_add_u32 m0, s100, 0xe000
	v_mfma_f32_16x16x32_bf16 v[210:213], v[132:135], v[118:121], v[54:57]
	global_load_lds_dwordx4 v7, s[98:99]
	v_mfma_f32_16x16x32_bf16 v[70:73], v[140:143], v[118:121], v[70:73]
	ds_read_b128 v[118:121], v130 offset:18432
	s_add_u32 m0, s100, 0xb000
	s_waitcnt lgkmcnt(6)
	v_mfma_f32_16x16x32_bf16 v[98:101], v[98:101], v[126:129], v[58:61]
	global_load_lds_dwordx4 v8, s[98:99]
	v_mfma_f32_16x16x32_bf16 v[66:69], v[110:113], v[126:129], v[66:69]
	ds_read_b128 v[110:113], v130 offset:20480
	s_add_u32 m0, s100, 0xf000
	v_mfma_f32_16x16x32_bf16 v[132:135], v[132:135], v[126:129], v[62:65]
	global_load_lds_dwordx4 v9, s[98:99]
	v_mfma_f32_16x16x32_bf16 v[74:77], v[140:143], v[126:129], v[74:77]
	ds_read_b128 v[126:129], v130 offset:22528
	s_waitcnt lgkmcnt(3)
	v_mfma_f32_16x16x32_bf16 v[140:143], v[206:209], v[148:151], v[144:147]
	s_waitcnt lgkmcnt(2)
	v_mfma_f32_16x16x32_bf16 v[94:97], v[118:121], v[148:151], v[94:97]
	s_waitcnt lgkmcnt(1)
	v_mfma_f32_16x16x32_bf16 v[144:147], v[110:113], v[148:151], v[158:161]
	s_waitcnt lgkmcnt(0)
	v_mfma_f32_16x16x32_bf16 v[90:93], v[126:129], v[148:151], v[90:93]
	v_mfma_f32_16x16x32_bf16 v[148:151], v[206:209], v[102:105], v[162:165]
	v_mfma_f32_16x16x32_bf16 v[86:89], v[118:121], v[102:105], v[86:89]
	v_mfma_f32_16x16x32_bf16 v[158:161], v[110:113], v[102:105], v[198:201]
	v_mfma_f32_16x16x32_bf16 v[82:85], v[126:129], v[102:105], v[82:85]
	v_mfma_f32_16x16x32_bf16 v[102:105], v[206:209], v[194:197], v[202:205]
	v_mfma_f32_16x16x32_bf16 v[78:81], v[118:121], v[194:197], v[78:81]
	v_mfma_f32_16x16x32_bf16 v[162:165], v[110:113], v[194:197], v[210:213]
	v_mfma_f32_16x16x32_bf16 v[70:73], v[126:129], v[194:197], v[70:73]
	v_mfma_f32_16x16x32_bf16 v[98:101], v[206:209], v[106:109], v[98:101]
	v_mfma_f32_16x16x32_bf16 v[66:69], v[118:121], v[106:109], v[66:69]
	v_mfma_f32_16x16x32_bf16 v[110:113], v[110:113], v[106:109], v[132:135]
	v_mfma_f32_16x16x32_bf16 v[74:77], v[126:129], v[106:109], v[74:77]
	s_waitcnt vmcnt(0)
	s_setprio 0
	s_waitcnt lgkmcnt(0)
	s_barrier
	s_setprio 1
	ds_read_b128 v[26:29], v122 offset:49152
	ds_read_b128 v[10:13], v124 offset:32768
	ds_read_b128 v[18:21], v124 offset:34816
	ds_read_b128 v[30:33], v122 offset:51200
	ds_read_b128 v[106:109], v124 offset:36864
	ds_read_b128 v[114:117], v124 offset:38912
	ds_read_b128 v[118:121], v122 offset:53248
	ds_read_b128 v[124:127], v122 offset:55296
	s_add_u32 m0, s100, 0x0
	s_waitcnt lgkmcnt(6)
	v_mfma_f32_16x16x32_bf16 v[132:135], v[26:29], v[10:13], v[140:143]
	global_load_lds_dwordx4 v[180:181], off
	s_waitcnt lgkmcnt(4)
	v_mfma_f32_16x16x32_bf16 v[94:97], v[30:33], v[10:13], v[94:97]
	ds_read_b128 v[140:143], v123 offset:32768
	s_add_u32 m0, s100, 0x4000
	s_waitcnt lgkmcnt(2)
	v_mfma_f32_16x16x32_bf16 v[144:147], v[118:121], v[10:13], v[144:147]
	global_load_lds_dwordx4 v[186:187], off
	s_waitcnt lgkmcnt(1)
	v_mfma_f32_16x16x32_bf16 v[90:93], v[124:127], v[10:13], v[90:93]
	ds_read_b128 v[194:197], v123 offset:34816
	s_add_u32 m0, s100, 0x1000
	v_mfma_f32_16x16x32_bf16 v[148:151], v[26:29], v[18:21], v[148:151]
	global_load_lds_dwordx4 v[188:189], off
	v_mfma_f32_16x16x32_bf16 v[86:89], v[30:33], v[18:21], v[86:89]
	ds_read_b128 v[198:201], v123 offset:36864
	s_add_u32 m0, s100, 0x5000
	v_mfma_f32_16x16x32_bf16 v[158:161], v[118:121], v[18:21], v[158:161]
	global_load_lds_dwordx4 v[174:175], off
	v_mfma_f32_16x16x32_bf16 v[82:85], v[124:127], v[18:21], v[82:85]
	ds_read_b128 v[202:205], v123 offset:38912
	s_add_u32 m0, s100, 0x2000
	v_mfma_f32_16x16x32_bf16 v[206:209], v[26:29], v[106:109], v[102:105]
	global_load_lds_dwordx4 v[136:137], off
	v_mfma_f32_16x16x32_bf16 v[78:81], v[30:33], v[106:109], v[78:81]
	ds_read_b128 v[210:213], v130 offset:49152
	s_add_u32 m0, s100, 0x6000
	v_mfma_f32_16x16x32_bf16 v[162:165], v[118:121], v[106:109], v[162:165]
	global_load_lds_dwordx4 v[176:177], off
	v_mfma_f32_16x16x32_bf16 v[70:73], v[124:127], v[106:109], v[70:73]
	ds_read_b128 v[214:217], v130 offset:51200
	s_add_u32 m0, s100, 0x3000
	v_mfma_f32_16x16x32_bf16 v[218:221], v[26:29], v[114:117], v[98:101]
	global_load_lds_dwordx4 v[166:167], off
	v_mfma_f32_16x16x32_bf16 v[66:69], v[30:33], v[114:117], v[66:69]
	ds_read_b128 v[222:225], v130 offset:53248
	s_add_u32 m0, s100, 0x7000
	v_mfma_f32_16x16x32_bf16 v[226:229], v[118:121], v[114:117], v[110:113]
	global_load_lds_dwordx4 v[178:179], off
	v_mfma_f32_16x16x32_bf16 v[230:233], v[124:127], v[114:117], v[74:77]
	s_waitcnt lgkmcnt(2)
	v_mfma_f32_16x16x32_bf16 v[126:129], v[210:213], v[140:143], v[132:135]
	ds_read_b128 v[130:133], v130 offset:55296
	s_waitcnt lgkmcnt(2)
	v_mfma_f32_16x16x32_bf16 v[122:125], v[214:217], v[140:143], v[94:97]
	s_waitcnt lgkmcnt(1)
	v_mfma_f32_16x16x32_bf16 v[118:121], v[222:225], v[140:143], v[144:147]
	s_waitcnt lgkmcnt(0)
	v_mfma_f32_16x16x32_bf16 v[114:117], v[130:133], v[140:143], v[90:93]
	v_mfma_f32_16x16x32_bf16 v[110:113], v[210:213], v[194:197], v[148:151]
	v_mfma_f32_16x16x32_bf16 v[106:109], v[214:217], v[194:197], v[86:89]
	v_mfma_f32_16x16x32_bf16 v[102:105], v[222:225], v[194:197], v[158:161]
	v_mfma_f32_16x16x32_bf16 v[98:101], v[130:133], v[194:197], v[82:85]
	v_mfma_f32_16x16x32_bf16 v[94:97], v[210:213], v[198:201], v[206:209]
	v_mfma_f32_16x16x32_bf16 v[90:93], v[214:217], v[198:201], v[78:81]
	v_mfma_f32_16x16x32_bf16 v[86:89], v[222:225], v[198:201], v[162:165]
	v_mfma_f32_16x16x32_bf16 v[82:85], v[130:133], v[198:201], v[70:73]
	v_mfma_f32_16x16x32_bf16 v[78:81], v[210:213], v[202:205], v[218:221]
	v_mfma_f32_16x16x32_bf16 v[74:77], v[214:217], v[202:205], v[66:69]
	v_mfma_f32_16x16x32_bf16 v[70:73], v[222:225], v[202:205], v[226:229]
	v_mfma_f32_16x16x32_bf16 v[66:69], v[130:133], v[202:205], v[230:233]
	s_setprio 0
	v_add_u32_e32 v134, s4, v152
	v_ashrrev_i32_e32 v135, 31, v134
	v_lshlrev_b64 v[136:137], 12, v[134:135]
	v_or_b32_e32 v140, s10, v153
	v_mov_b32_e32 v141, v1
	v_cndmask_b32_e64 v0, 0, 1, s[42:43]
	v_lshl_add_u64 v[130:131], s[40:41], 0, v[136:137]
	v_cmp_ne_u32_e64 s[38:39], 1, v0
	s_andn2_b64 vcc, exec, s[42:43]
	v_lshl_add_u64 v[146:147], v[140:141], 2, v[130:131]
	s_barrier
	v_readlane_b32 s48, v253, 18
	v_readlane_b32 s49, v253, 19
	v_readlane_b32 s50, v253, 20
	v_readlane_b32 s51, v253, 21
	v_readlane_b32 s52, v253, 22
	v_readlane_b32 s53, v253, 23
	v_readlane_b32 s54, v253, 24
	v_readlane_b32 s55, v253, 25
	v_readlane_b32 s56, v253, 26
	v_readlane_b32 s57, v253, 27
	v_readlane_b32 s58, v253, 28
	v_readlane_b32 s59, v253, 29
	v_readlane_b32 s60, v253, 30
	v_readlane_b32 s61, v253, 31
	v_readlane_b32 s62, v253, 32
	v_readlane_b32 s63, v253, 33
	v_or_b32_e32 v0, s10, v153
	v_lshlrev_b32_e32 v0, 2, v0
	v_add_u32_e32 v130, s4, v152
	v_lshlrev_b32_e32 v50, 3, v130
	v_lshlrev_b32_e32 v130, 12, v130
	v_add_u32_e32 v130, v130, v0
	v_add_u32_e32 v131, s4, v154
	v_lshlrev_b32_e32 v54, 3, v131
	v_lshlrev_b32_e32 v131, 12, v131
	v_add_u32_e32 v131, v131, v0
	v_add_u32_e32 v132, s4, v155
	v_lshlrev_b32_e32 v58, 3, v132
	v_lshlrev_b32_e32 v132, 12, v132
	v_add_u32_e32 v132, v132, v0
	v_add_u32_e32 v133, s4, v156
	v_lshlrev_b32_e32 v62, 3, v133
	v_lshlrev_b32_e32 v133, 12, v133
	v_add_u32_e32 v133, v133, v0
	s_mov_b32 s10, 0x3fb504f3
	s_cmp_lg_u64 s[40:41], 0
	s_cbranch_scc0 .Lepi_ln_157
	global_load_dwordx4 v[2:5], v130, s[40:41]
	global_load_dwordx4 v[6:9], v131, s[40:41]
	global_load_dwordx4 v[10:13], v132, s[40:41]
	global_load_dwordx4 v[14:17], v133, s[40:41]
	global_load_dwordx4 v[18:21], v130, s[40:41] offset:16
	global_load_dwordx4 v[22:25], v131, s[40:41] offset:16
	global_load_dwordx4 v[26:29], v132, s[40:41] offset:16
	global_load_dwordx4 v[30:33], v133, s[40:41] offset:16
	global_load_dwordx4 v[34:37], v130, s[40:41] offset:128
	global_load_dwordx4 v[38:41], v131, s[40:41] offset:128
	global_load_dwordx4 v[42:45], v132, s[40:41] offset:128
	global_load_dwordx4 v[46:49], v133, s[40:41] offset:128
	global_load_dwordx4 v[50:53], v130, s[40:41] offset:144
	global_load_dwordx4 v[54:57], v131, s[40:41] offset:144
	global_load_dwordx4 v[58:61], v132, s[40:41] offset:144
	global_load_dwordx4 v[62:65], v133, s[40:41] offset:144
	s_waitcnt vmcnt(15)
	v_pk_fma_f32 v[126:127], v[2:3], s[10:11], v[126:127] op_sel_hi:[1,0,1]
	v_pk_fma_f32 v[128:129], v[4:5], s[10:11], v[128:129] op_sel_hi:[1,0,1]
	global_store_dwordx4 v130, v[126:129], s[62:63]
	s_waitcnt vmcnt(15)
	v_pk_fma_f32 v[110:111], v[6:7], s[10:11], v[110:111] op_sel_hi:[1,0,1]
	v_pk_fma_f32 v[112:113], v[8:9], s[10:11], v[112:113] op_sel_hi:[1,0,1]
	global_store_dwordx4 v131, v[110:113], s[62:63]
	s_waitcnt vmcnt(15)
	v_pk_fma_f32 v[94:95], v[10:11], s[10:11], v[94:95] op_sel_hi:[1,0,1]
	v_pk_fma_f32 v[96:97], v[12:13], s[10:11], v[96:97] op_sel_hi:[1,0,1]
	global_store_dwordx4 v132, v[94:97], s[62:63]
	s_waitcnt vmcnt(15)
	v_pk_fma_f32 v[78:79], v[14:15], s[10:11], v[78:79] op_sel_hi:[1,0,1]
	v_pk_fma_f32 v[80:81], v[16:17], s[10:11], v[80:81] op_sel_hi:[1,0,1]
	global_store_dwordx4 v133, v[78:81], s[62:63]
	s_waitcnt vmcnt(15)
	v_pk_fma_f32 v[122:123], v[18:19], s[10:11], v[122:123] op_sel_hi:[1,0,1]
	v_pk_fma_f32 v[124:125], v[20:21], s[10:11], v[124:125] op_sel_hi:[1,0,1]
	global_store_dwordx4 v130, v[122:125], s[62:63] offset:16
	s_waitcnt vmcnt(15)
	v_pk_fma_f32 v[106:107], v[22:23], s[10:11], v[106:107] op_sel_hi:[1,0,1]
	v_pk_fma_f32 v[108:109], v[24:25], s[10:11], v[108:109] op_sel_hi:[1,0,1]
	global_store_dwordx4 v131, v[106:109], s[62:63] offset:16
	s_waitcnt vmcnt(15)
	v_pk_fma_f32 v[90:91], v[26:27], s[10:11], v[90:91] op_sel_hi:[1,0,1]
	v_pk_fma_f32 v[92:93], v[28:29], s[10:11], v[92:93] op_sel_hi:[1,0,1]
	global_store_dwordx4 v132, v[90:93], s[62:63] offset:16
	s_waitcnt vmcnt(15)
	v_pk_fma_f32 v[74:75], v[30:31], s[10:11], v[74:75] op_sel_hi:[1,0,1]
	v_pk_fma_f32 v[76:77], v[32:33], s[10:11], v[76:77] op_sel_hi:[1,0,1]
	global_store_dwordx4 v133, v[74:77], s[62:63] offset:16
	s_waitcnt vmcnt(15)
	v_pk_fma_f32 v[118:119], v[34:35], s[10:11], v[118:119] op_sel_hi:[1,0,1]
	v_pk_fma_f32 v[120:121], v[36:37], s[10:11], v[120:121] op_sel_hi:[1,0,1]
	global_store_dwordx4 v130, v[118:121], s[62:63] offset:128
	s_waitcnt vmcnt(15)
	v_pk_fma_f32 v[102:103], v[38:39], s[10:11], v[102:103] op_sel_hi:[1,0,1]
	v_pk_fma_f32 v[104:105], v[40:41], s[10:11], v[104:105] op_sel_hi:[1,0,1]
	global_store_dwordx4 v131, v[102:105], s[62:63] offset:128
	s_waitcnt vmcnt(15)
	v_pk_fma_f32 v[86:87], v[42:43], s[10:11], v[86:87] op_sel_hi:[1,0,1]
	v_pk_fma_f32 v[88:89], v[44:45], s[10:11], v[88:89] op_sel_hi:[1,0,1]
	global_store_dwordx4 v132, v[86:89], s[62:63] offset:128
	s_waitcnt vmcnt(15)
	v_pk_fma_f32 v[70:71], v[46:47], s[10:11], v[70:71] op_sel_hi:[1,0,1]
	v_pk_fma_f32 v[72:73], v[48:49], s[10:11], v[72:73] op_sel_hi:[1,0,1]
	global_store_dwordx4 v133, v[70:73], s[62:63] offset:128
	s_waitcnt vmcnt(15)
	v_pk_fma_f32 v[114:115], v[50:51], s[10:11], v[114:115] op_sel_hi:[1,0,1]
	v_pk_fma_f32 v[116:117], v[52:53], s[10:11], v[116:117] op_sel_hi:[1,0,1]
	global_store_dwordx4 v130, v[114:117], s[62:63] offset:144
	s_waitcnt vmcnt(15)
	v_pk_fma_f32 v[98:99], v[54:55], s[10:11], v[98:99] op_sel_hi:[1,0,1]
	v_pk_fma_f32 v[100:101], v[56:57], s[10:11], v[100:101] op_sel_hi:[1,0,1]
	global_store_dwordx4 v131, v[98:101], s[62:63] offset:144
	s_waitcnt vmcnt(15)
	v_pk_fma_f32 v[82:83], v[58:59], s[10:11], v[82:83] op_sel_hi:[1,0,1]
	v_pk_fma_f32 v[84:85], v[60:61], s[10:11], v[84:85] op_sel_hi:[1,0,1]
	global_store_dwordx4 v132, v[82:85], s[62:63] offset:144
	s_waitcnt vmcnt(15)
	v_pk_fma_f32 v[66:67], v[62:63], s[10:11], v[66:67] op_sel_hi:[1,0,1]
	v_pk_fma_f32 v[68:69], v[64:65], s[10:11], v[68:69] op_sel_hi:[1,0,1]
	global_store_dwordx4 v133, v[66:69], s[62:63] offset:144
	s_branch .Lepi_done_157
.Lepi_ln_157:
	global_load_dwordx2 v[134:135], v50, s[0:1]
	global_load_dwordx2 v[136:137], v54, s[0:1]
	global_load_dwordx2 v[140:141], v58, s[0:1]
	global_load_dwordx2 v[142:143], v62, s[0:1]
	global_load_dwordx4 v[144:147], v0, s[58:59]
	global_load_dwordx4 v[234:237], v0, s[60:61]
	global_load_dwordx4 v[2:5], v130, s[62:63]
	global_load_dwordx4 v[6:9], v131, s[62:63]
	global_load_dwordx4 v[10:13], v132, s[62:63]
	global_load_dwordx4 v[14:17], v133, s[62:63]
	global_load_dwordx4 v[148:151], v0, s[58:59] offset:16
	global_load_dwordx4 v[238:241], v0, s[60:61] offset:16
	global_load_dwordx4 v[18:21], v130, s[62:63] offset:16
	global_load_dwordx4 v[22:25], v131, s[62:63] offset:16
	global_load_dwordx4 v[26:29], v132, s[62:63] offset:16
	global_load_dwordx4 v[30:33], v133, s[62:63] offset:16
	global_load_dwordx4 v[158:161], v0, s[58:59] offset:128
	global_load_dwordx4 v[242:245], v0, s[60:61] offset:128
	global_load_dwordx4 v[34:37], v130, s[62:63] offset:128
	global_load_dwordx4 v[38:41], v131, s[62:63] offset:128
	global_load_dwordx4 v[42:45], v132, s[62:63] offset:128
	global_load_dwordx4 v[46:49], v133, s[62:63] offset:128
	global_load_dwordx4 v[162:165], v0, s[58:59] offset:144
	global_load_dwordx4 v[246:249], v0, s[60:61] offset:144
	global_load_dwordx4 v[50:53], v130, s[62:63] offset:144
	global_load_dwordx4 v[54:57], v131, s[62:63] offset:144
	global_load_dwordx4 v[58:61], v132, s[62:63] offset:144
	global_load_dwordx4 v[62:65], v133, s[62:63] offset:144
	s_waitcnt vmcnt(21)
	v_pk_add_f32 v[2:3], v[2:3], v[134:135] op_sel_hi:[1,0] neg_lo:[0,1] neg_hi:[0,1]
	v_pk_add_f32 v[4:5], v[4:5], v[134:135] op_sel_hi:[1,0] neg_lo:[0,1] neg_hi:[0,1]
	v_pk_mul_f32 v[2:3], v[2:3], v[134:135] op_sel:[0,1]
	v_pk_mul_f32 v[4:5], v[4:5], v[134:135] op_sel:[0,1]
	v_pk_fma_f32 v[2:3], v[2:3], v[144:145], v[234:235]
	v_pk_fma_f32 v[4:5], v[4:5], v[146:147], v[236:237]
	v_pk_fma_f32 v[126:127], v[2:3], s[10:11], v[126:127] op_sel_hi:[1,0,1]
	v_pk_fma_f32 v[128:129], v[4:5], s[10:11], v[128:129] op_sel_hi:[1,0,1]
	global_store_dwordx4 v130, v[126:129], s[62:63]
	s_waitcnt vmcnt(21)
	v_pk_add_f32 v[6:7], v[6:7], v[136:137] op_sel_hi:[1,0] neg_lo:[0,1] neg_hi:[0,1]
	v_pk_add_f32 v[8:9], v[8:9], v[136:137] op_sel_hi:[1,0] neg_lo:[0,1] neg_hi:[0,1]
	v_pk_mul_f32 v[6:7], v[6:7], v[136:137] op_sel:[0,1]
	v_pk_mul_f32 v[8:9], v[8:9], v[136:137] op_sel:[0,1]
	v_pk_fma_f32 v[6:7], v[6:7], v[144:145], v[234:235]
	v_pk_fma_f32 v[8:9], v[8:9], v[146:147], v[236:237]
	v_pk_fma_f32 v[110:111], v[6:7], s[10:11], v[110:111] op_sel_hi:[1,0,1]
	v_pk_fma_f32 v[112:113], v[8:9], s[10:11], v[112:113] op_sel_hi:[1,0,1]
	global_store_dwordx4 v131, v[110:113], s[62:63]
	s_waitcnt vmcnt(21)
	v_pk_add_f32 v[10:11], v[10:11], v[140:141] op_sel_hi:[1,0] neg_lo:[0,1] neg_hi:[0,1]
	v_pk_add_f32 v[12:13], v[12:13], v[140:141] op_sel_hi:[1,0] neg_lo:[0,1] neg_hi:[0,1]
	v_pk_mul_f32 v[10:11], v[10:11], v[140:141] op_sel:[0,1]
	v_pk_mul_f32 v[12:13], v[12:13], v[140:141] op_sel:[0,1]
	v_pk_fma_f32 v[10:11], v[10:11], v[144:145], v[234:235]
	v_pk_fma_f32 v[12:13], v[12:13], v[146:147], v[236:237]
	v_pk_fma_f32 v[94:95], v[10:11], s[10:11], v[94:95] op_sel_hi:[1,0,1]
	v_pk_fma_f32 v[96:97], v[12:13], s[10:11], v[96:97] op_sel_hi:[1,0,1]
	global_store_dwordx4 v132, v[94:97], s[62:63]
	s_waitcnt vmcnt(21)
	v_pk_add_f32 v[14:15], v[14:15], v[142:143] op_sel_hi:[1,0] neg_lo:[0,1] neg_hi:[0,1]
	v_pk_add_f32 v[16:17], v[16:17], v[142:143] op_sel_hi:[1,0] neg_lo:[0,1] neg_hi:[0,1]
	v_pk_mul_f32 v[14:15], v[14:15], v[142:143] op_sel:[0,1]
	v_pk_mul_f32 v[16:17], v[16:17], v[142:143] op_sel:[0,1]
	v_pk_fma_f32 v[14:15], v[14:15], v[144:145], v[234:235]
	v_pk_fma_f32 v[16:17], v[16:17], v[146:147], v[236:237]
	v_pk_fma_f32 v[78:79], v[14:15], s[10:11], v[78:79] op_sel_hi:[1,0,1]
	v_pk_fma_f32 v[80:81], v[16:17], s[10:11], v[80:81] op_sel_hi:[1,0,1]
	global_store_dwordx4 v133, v[78:81], s[62:63]
	s_waitcnt vmcnt(19)
	v_pk_add_f32 v[18:19], v[18:19], v[134:135] op_sel_hi:[1,0] neg_lo:[0,1] neg_hi:[0,1]
	v_pk_add_f32 v[20:21], v[20:21], v[134:135] op_sel_hi:[1,0] neg_lo:[0,1] neg_hi:[0,1]
	v_pk_mul_f32 v[18:19], v[18:19], v[134:135] op_sel:[0,1]
	v_pk_mul_f32 v[20:21], v[20:21], v[134:135] op_sel:[0,1]
	v_pk_fma_f32 v[18:19], v[18:19], v[148:149], v[238:239]
	v_pk_fma_f32 v[20:21], v[20:21], v[150:151], v[240:241]
	v_pk_fma_f32 v[122:123], v[18:19], s[10:11], v[122:123] op_sel_hi:[1,0,1]
	v_pk_fma_f32 v[124:125], v[20:21], s[10:11], v[124:125] op_sel_hi:[1,0,1]
	global_store_dwordx4 v130, v[122:125], s[62:63] offset:16
	s_waitcnt vmcnt(19)
	v_pk_add_f32 v[22:23], v[22:23], v[136:137] op_sel_hi:[1,0] neg_lo:[0,1] neg_hi:[0,1]
	v_pk_add_f32 v[24:25], v[24:25], v[136:137] op_sel_hi:[1,0] neg_lo:[0,1] neg_hi:[0,1]
	v_pk_mul_f32 v[22:23], v[22:23], v[136:137] op_sel:[0,1]
	v_pk_mul_f32 v[24:25], v[24:25], v[136:137] op_sel:[0,1]
	v_pk_fma_f32 v[22:23], v[22:23], v[148:149], v[238:239]
	v_pk_fma_f32 v[24:25], v[24:25], v[150:151], v[240:241]
	v_pk_fma_f32 v[106:107], v[22:23], s[10:11], v[106:107] op_sel_hi:[1,0,1]
	v_pk_fma_f32 v[108:109], v[24:25], s[10:11], v[108:109] op_sel_hi:[1,0,1]
	global_store_dwordx4 v131, v[106:109], s[62:63] offset:16
	s_waitcnt vmcnt(19)
	v_pk_add_f32 v[26:27], v[26:27], v[140:141] op_sel_hi:[1,0] neg_lo:[0,1] neg_hi:[0,1]
	v_pk_add_f32 v[28:29], v[28:29], v[140:141] op_sel_hi:[1,0] neg_lo:[0,1] neg_hi:[0,1]
	v_pk_mul_f32 v[26:27], v[26:27], v[140:141] op_sel:[0,1]
	v_pk_mul_f32 v[28:29], v[28:29], v[140:141] op_sel:[0,1]
	v_pk_fma_f32 v[26:27], v[26:27], v[148:149], v[238:239]
	v_pk_fma_f32 v[28:29], v[28:29], v[150:151], v[240:241]
	v_pk_fma_f32 v[90:91], v[26:27], s[10:11], v[90:91] op_sel_hi:[1,0,1]
	v_pk_fma_f32 v[92:93], v[28:29], s[10:11], v[92:93] op_sel_hi:[1,0,1]
	global_store_dwordx4 v132, v[90:93], s[62:63] offset:16
	s_waitcnt vmcnt(19)
	v_pk_add_f32 v[30:31], v[30:31], v[142:143] op_sel_hi:[1,0] neg_lo:[0,1] neg_hi:[0,1]
	v_pk_add_f32 v[32:33], v[32:33], v[142:143] op_sel_hi:[1,0] neg_lo:[0,1] neg_hi:[0,1]
	v_pk_mul_f32 v[30:31], v[30:31], v[142:143] op_sel:[0,1]
	v_pk_mul_f32 v[32:33], v[32:33], v[142:143] op_sel:[0,1]
	v_pk_fma_f32 v[30:31], v[30:31], v[148:149], v[238:239]
	v_pk_fma_f32 v[32:33], v[32:33], v[150:151], v[240:241]
	v_pk_fma_f32 v[74:75], v[30:31], s[10:11], v[74:75] op_sel_hi:[1,0,1]
	v_pk_fma_f32 v[76:77], v[32:33], s[10:11], v[76:77] op_sel_hi:[1,0,1]
	global_store_dwordx4 v133, v[74:77], s[62:63] offset:16
	s_waitcnt vmcnt(17)
	v_pk_add_f32 v[34:35], v[34:35], v[134:135] op_sel_hi:[1,0] neg_lo:[0,1] neg_hi:[0,1]
	v_pk_add_f32 v[36:37], v[36:37], v[134:135] op_sel_hi:[1,0] neg_lo:[0,1] neg_hi:[0,1]
	v_pk_mul_f32 v[34:35], v[34:35], v[134:135] op_sel:[0,1]
	v_pk_mul_f32 v[36:37], v[36:37], v[134:135] op_sel:[0,1]
	v_pk_fma_f32 v[34:35], v[34:35], v[158:159], v[242:243]
	v_pk_fma_f32 v[36:37], v[36:37], v[160:161], v[244:245]
	v_pk_fma_f32 v[118:119], v[34:35], s[10:11], v[118:119] op_sel_hi:[1,0,1]
	v_pk_fma_f32 v[120:121], v[36:37], s[10:11], v[120:121] op_sel_hi:[1,0,1]
	global_store_dwordx4 v130, v[118:121], s[62:63] offset:128
	s_waitcnt vmcnt(17)
	v_pk_add_f32 v[38:39], v[38:39], v[136:137] op_sel_hi:[1,0] neg_lo:[0,1] neg_hi:[0,1]
	v_pk_add_f32 v[40:41], v[40:41], v[136:137] op_sel_hi:[1,0] neg_lo:[0,1] neg_hi:[0,1]
	v_pk_mul_f32 v[38:39], v[38:39], v[136:137] op_sel:[0,1]
	v_pk_mul_f32 v[40:41], v[40:41], v[136:137] op_sel:[0,1]
	v_pk_fma_f32 v[38:39], v[38:39], v[158:159], v[242:243]
	v_pk_fma_f32 v[40:41], v[40:41], v[160:161], v[244:245]
	v_pk_fma_f32 v[102:103], v[38:39], s[10:11], v[102:103] op_sel_hi:[1,0,1]
	v_pk_fma_f32 v[104:105], v[40:41], s[10:11], v[104:105] op_sel_hi:[1,0,1]
	global_store_dwordx4 v131, v[102:105], s[62:63] offset:128
	s_waitcnt vmcnt(17)
	v_pk_add_f32 v[42:43], v[42:43], v[140:141] op_sel_hi:[1,0] neg_lo:[0,1] neg_hi:[0,1]
	v_pk_add_f32 v[44:45], v[44:45], v[140:141] op_sel_hi:[1,0] neg_lo:[0,1] neg_hi:[0,1]
	v_pk_mul_f32 v[42:43], v[42:43], v[140:141] op_sel:[0,1]
	v_pk_mul_f32 v[44:45], v[44:45], v[140:141] op_sel:[0,1]
	v_pk_fma_f32 v[42:43], v[42:43], v[158:159], v[242:243]
	v_pk_fma_f32 v[44:45], v[44:45], v[160:161], v[244:245]
	v_pk_fma_f32 v[86:87], v[42:43], s[10:11], v[86:87] op_sel_hi:[1,0,1]
	v_pk_fma_f32 v[88:89], v[44:45], s[10:11], v[88:89] op_sel_hi:[1,0,1]
	global_store_dwordx4 v132, v[86:89], s[62:63] offset:128
	s_waitcnt vmcnt(17)
	v_pk_add_f32 v[46:47], v[46:47], v[142:143] op_sel_hi:[1,0] neg_lo:[0,1] neg_hi:[0,1]
	v_pk_add_f32 v[48:49], v[48:49], v[142:143] op_sel_hi:[1,0] neg_lo:[0,1] neg_hi:[0,1]
	v_pk_mul_f32 v[46:47], v[46:47], v[142:143] op_sel:[0,1]
	v_pk_mul_f32 v[48:49], v[48:49], v[142:143] op_sel:[0,1]
	v_pk_fma_f32 v[46:47], v[46:47], v[158:159], v[242:243]
	v_pk_fma_f32 v[48:49], v[48:49], v[160:161], v[244:245]
	v_pk_fma_f32 v[70:71], v[46:47], s[10:11], v[70:71] op_sel_hi:[1,0,1]
	v_pk_fma_f32 v[72:73], v[48:49], s[10:11], v[72:73] op_sel_hi:[1,0,1]
	global_store_dwordx4 v133, v[70:73], s[62:63] offset:128
	s_waitcnt vmcnt(15)
	v_pk_add_f32 v[50:51], v[50:51], v[134:135] op_sel_hi:[1,0] neg_lo:[0,1] neg_hi:[0,1]
	v_pk_add_f32 v[52:53], v[52:53], v[134:135] op_sel_hi:[1,0] neg_lo:[0,1] neg_hi:[0,1]
	v_pk_mul_f32 v[50:51], v[50:51], v[134:135] op_sel:[0,1]
	v_pk_mul_f32 v[52:53], v[52:53], v[134:135] op_sel:[0,1]
	v_pk_fma_f32 v[50:51], v[50:51], v[162:163], v[246:247]
	v_pk_fma_f32 v[52:53], v[52:53], v[164:165], v[248:249]
	v_pk_fma_f32 v[114:115], v[50:51], s[10:11], v[114:115] op_sel_hi:[1,0,1]
	v_pk_fma_f32 v[116:117], v[52:53], s[10:11], v[116:117] op_sel_hi:[1,0,1]
	global_store_dwordx4 v130, v[114:117], s[62:63] offset:144
	s_waitcnt vmcnt(15)
	v_pk_add_f32 v[54:55], v[54:55], v[136:137] op_sel_hi:[1,0] neg_lo:[0,1] neg_hi:[0,1]
	v_pk_add_f32 v[56:57], v[56:57], v[136:137] op_sel_hi:[1,0] neg_lo:[0,1] neg_hi:[0,1]
	v_pk_mul_f32 v[54:55], v[54:55], v[136:137] op_sel:[0,1]
	v_pk_mul_f32 v[56:57], v[56:57], v[136:137] op_sel:[0,1]
	v_pk_fma_f32 v[54:55], v[54:55], v[162:163], v[246:247]
	v_pk_fma_f32 v[56:57], v[56:57], v[164:165], v[248:249]
	v_pk_fma_f32 v[98:99], v[54:55], s[10:11], v[98:99] op_sel_hi:[1,0,1]
	v_pk_fma_f32 v[100:101], v[56:57], s[10:11], v[100:101] op_sel_hi:[1,0,1]
	global_store_dwordx4 v131, v[98:101], s[62:63] offset:144
	s_waitcnt vmcnt(15)
	v_pk_add_f32 v[58:59], v[58:59], v[140:141] op_sel_hi:[1,0] neg_lo:[0,1] neg_hi:[0,1]
	v_pk_add_f32 v[60:61], v[60:61], v[140:141] op_sel_hi:[1,0] neg_lo:[0,1] neg_hi:[0,1]
	v_pk_mul_f32 v[58:59], v[58:59], v[140:141] op_sel:[0,1]
	v_pk_mul_f32 v[60:61], v[60:61], v[140:141] op_sel:[0,1]
	v_pk_fma_f32 v[58:59], v[58:59], v[162:163], v[246:247]
	v_pk_fma_f32 v[60:61], v[60:61], v[164:165], v[248:249]
	v_pk_fma_f32 v[82:83], v[58:59], s[10:11], v[82:83] op_sel_hi:[1,0,1]
	v_pk_fma_f32 v[84:85], v[60:61], s[10:11], v[84:85] op_sel_hi:[1,0,1]
	global_store_dwordx4 v132, v[82:85], s[62:63] offset:144
	s_waitcnt vmcnt(15)
	v_pk_add_f32 v[62:63], v[62:63], v[142:143] op_sel_hi:[1,0] neg_lo:[0,1] neg_hi:[0,1]
	v_pk_add_f32 v[64:65], v[64:65], v[142:143] op_sel_hi:[1,0] neg_lo:[0,1] neg_hi:[0,1]
	v_pk_mul_f32 v[62:63], v[62:63], v[142:143] op_sel:[0,1]
	v_pk_mul_f32 v[64:65], v[64:65], v[142:143] op_sel:[0,1]
	v_pk_fma_f32 v[62:63], v[62:63], v[162:163], v[246:247]
	v_pk_fma_f32 v[64:65], v[64:65], v[164:165], v[248:249]
	v_pk_fma_f32 v[66:67], v[62:63], s[10:11], v[66:67] op_sel_hi:[1,0,1]
	v_pk_fma_f32 v[68:69], v[64:65], s[10:11], v[68:69] op_sel_hi:[1,0,1]
	global_store_dwordx4 v133, v[66:69], s[62:63] offset:144
